# hand-written prep_dn_chunk: wave owns 8 rows x 3 sections, sliding-window conv, in-place progressive prefetch, packed f32 + DPP l2norm
# speedup vs baseline: 1.0307x; 1.0107x over previous
;     template <class Tp> __device__ __forceinline__ Tp* W(size_t off) const { return (Tp*)(ws + off); }
; __device__ __forceinline__ void prep_dn_load(const bf16_t* proj, const float* cw, int idx, u32x4 (&raw)[4], int& t, int& ch) {
;     if (idx >= 0) { t = idx / 384; const int j = idx - t * 384; ch = j * 8; }
; #pragma unroll
;     for (int k = 0; k < 4; ++k) { const int tt = t - 3 + k; raw[k] = (u32x4){0u, 0u, 0u, 0u};
;         if (tt >= 0) raw[k] = *(const u32x4*)(proj + (size_t)tt * NP + C_DNQ + ch); }
; __device__ void prep_dn_chunk(const Ctx& c, int ck, int half) {
;     const bf16_t* proj = c.W<bf16_t>(WS_PROJ);
;     const float* cw = c.in(I_DNCONV) + (size_t)c.layer * 4 * 3072;
;     bf16_t* dq = c.W<bf16_t>(WS_DQ); bf16_t* dk = c.W<bf16_t>(WS_DK); bf16_t* dv = c.W<bf16_t>(WS_DV);
;     for (int it = c.tid; it < 64 * 192; it += 1024) {
;         u32x4 r0[4], r1[4]; int t0, c0, t1, c1;
;         { const int l = it / 192, j = it - l * 192; t0 = ck * 64 + l; c0 = (j >> 6) * 1024 + half * 512 + (j & 63) * 8; }
;         { const int i2 = it + 512, l = i2 / 192, j = i2 - l * 192; t1 = ck * 64 + l; c1 = (j >> 6) * 1024 + half * 512 + (j & 63) * 8; }
;         prep_dn_load(proj, cw, -1, r0, t0, c0);
.LBB0_613:
	s_or_saveexec_b64 s[0:1], s[0:1]
	s_ashr_i32 s4, s18, 1
	s_mov_b32 s2, s4
	v_writelane_b32 v249, s2, 38
	s_lshl_b32 s20, s4, 6
	s_nop 0
	v_writelane_b32 v249, s3, 39
	s_xor_b64 exec, exec, s[0:1]
	s_cbranch_execz .LBB0_637
	v_and_b32_e32 v49, 64, v237
	v_xor_b32_e32 v0, 1, v237
	v_add_u32_e32 v1, 64, v49
	v_cmp_lt_i32_e32 vcc, v0, v1
	s_load_dwordx2 s[2:3], s[94:95], 0x20
	v_readlane_b32 s4, v248, 40
	v_cndmask_b32_e32 v0, v237, v0, vcc
	v_lshlrev_b32_e32 v55, 2, v0
	v_xor_b32_e32 v0, 2, v237
	v_cmp_lt_i32_e32 vcc, v0, v1
	s_waitcnt lgkmcnt(0)
	s_add_u32 s4, s2, s4
	v_readlane_b32 s2, v248, 39
	v_cndmask_b32_e32 v0, v237, v0, vcc
	v_lshlrev_b32_e32 v64, 2, v0
	v_xor_b32_e32 v0, 4, v237
	v_cmp_lt_i32_e32 vcc, v0, v1
	s_addc_u32 s5, s3, s2
	v_readlane_b32 s2, v249, 37
	v_cndmask_b32_e32 v0, v237, v0, vcc
	v_lshlrev_b32_e32 v65, 2, v0
	v_xor_b32_e32 v0, 8, v237
	v_cmp_lt_i32_e32 vcc, v0, v1
	v_readlane_b32 s14, v248, 41
	s_lshl_b32 s2, s2, 9
	v_cndmask_b32_e32 v0, v237, v0, vcc
	v_lshlrev_b32_e32 v66, 2, v0
	v_lshlrev_b32_e32 v48, 4, v144
	v_lshlrev_b32_e32 v67, 3, v144
	s_mov_b64 s[6:7], 0
	v_mov_b32_e32 v68, v144
	v_readlane_b32 s15, v248, 42
	s_load_dwordx2 s[8:9], s[94:95], 0xe8
	v_lshrrev_b32_e32 v7, 6, v144
	s_mov_b32 s12, 0xbfb8aa3b
	v_readfirstlane_b32 s11, v7
	s_mov_b32 s13, 0xbfb8aa3b
	s_mov_b32 s14, 1.0
	s_mov_b32 s15, 1.0
	v_lshlrev_b32_e32 v7, 3, v237
	v_add_u32_e32 v7, s2, v7
	v_lshlrev_b32_e32 v0, 1, v7
	v_lshlrev_b32_e32 v3, 2, v7
	v_add_u32_e32 v1, 0x800, v0
	v_add_u32_e32 v2, 0x1000, v0
	v_add_u32_e32 v4, 0x1f100000, v0
	v_add_u32_e32 v5, 0x20100000, v0
	v_add_u32_e32 v6, 0x21100000, v0
	s_lshl_b32 s3, s11, 3
	s_add_u32 s3, s3, s20
	s_add_i32 s10, s3, -3
	s_lshl_b32 s3, s3, 11
	s_waitcnt lgkmcnt(0)
	s_add_u32 s6, s8, s3
	s_addc_u32 s7, s9, 0
	s_mul_i32 s3, s10, 0x7e00
	s_ashr_i32 vcc_lo, s3, 31
	s_add_u32 s100, s8, s3
	s_addc_u32 s101, s9, vcc_lo
	s_add_u32 s100, s100, 0x9c00000
	s_addc_u32 s101, s101, 0
	global_load_dwordx4 v[96:99], v3, s[4:5]
	global_load_dwordx4 v[100:103], v3, s[4:5] offset:16
	s_add_u32 vcc_lo, s4, 0x3000
	s_addc_u32 vcc_hi, s5, 0
	global_load_dwordx4 v[104:107], v3, vcc
	global_load_dwordx4 v[108:111], v3, vcc offset:16
	s_add_u32 vcc_lo, s4, 0x6000
	s_addc_u32 vcc_hi, s5, 0
	global_load_dwordx4 v[112:115], v3, vcc
	global_load_dwordx4 v[116:119], v3, vcc offset:16
	s_add_u32 vcc_lo, s4, 0x9000
	s_addc_u32 vcc_hi, s5, 0
	global_load_dwordx4 v[120:123], v3, vcc
	global_load_dwordx4 v[124:127], v3, vcc offset:16
	global_load_dwordx4 v[52:55], v0, s[100:101]
	s_add_u32 s100, s100, 0x7e00
	s_addc_u32 s101, s101, 0
	global_load_dwordx4 v[56:59], v0, s[100:101]
	s_add_u32 s100, s100, 0x7e00
	s_addc_u32 s101, s101, 0
	global_load_dwordx4 v[60:63], v0, s[100:101]
	s_add_u32 s100, s100, 0x7e00
	s_addc_u32 s101, s101, 0
	global_load_dwordx4 v[64:67], v0, s[100:101]
	s_add_u32 s100, s100, 0x7e00
	s_addc_u32 s101, s101, 0
	global_load_dwordx4 v[68:71], v0, s[100:101]
	s_add_u32 s100, s100, 0x7e00
	s_addc_u32 s101, s101, 0
	global_load_dwordx4 v[72:75], v0, s[100:101]
	s_add_u32 s100, s100, 0x7e00
	s_addc_u32 s101, s101, 0
	global_load_dwordx4 v[76:79], v0, s[100:101]
	s_add_u32 s100, s100, 0x7e00
	s_addc_u32 s101, s101, 0
	global_load_dwordx4 v[80:83], v0, s[100:101]
	s_add_u32 s100, s100, 0x7e00
	s_addc_u32 s101, s101, 0
	global_load_dwordx4 v[84:87], v0, s[100:101]
	s_add_u32 s100, s100, 0x7e00
	s_addc_u32 s101, s101, 0
	global_load_dwordx4 v[88:91], v0, s[100:101]
	s_add_u32 s100, s100, 0x7e00
	s_addc_u32 s101, s101, 0
	global_load_dwordx4 v[92:95], v0, s[100:101]
	s_sub_u32 s100, s100, 0x4ec00
	s_subb_u32 s101, s101, 0
	s_add_u32 vcc_lo, s4, 0x1000
	s_addc_u32 vcc_hi, s5, 0
	global_load_dwordx4 v[8:11], v3, vcc
	global_load_dwordx4 v[12:15], v3, vcc offset:16
	s_add_u32 vcc_lo, s4, 0x4000
	s_addc_u32 vcc_hi, s5, 0
	global_load_dwordx4 v[16:19], v3, vcc
	global_load_dwordx4 v[20:23], v3, vcc offset:16
	s_add_u32 vcc_lo, s4, 0x7000
	s_addc_u32 vcc_hi, s5, 0
	global_load_dwordx4 v[24:27], v3, vcc
	global_load_dwordx4 v[28:31], v3, vcc offset:16
	s_add_u32 vcc_lo, s4, 0xa000
	s_addc_u32 vcc_hi, s5, 0
	global_load_dwordx4 v[32:35], v3, vcc
	global_load_dwordx4 v[36:39], v3, vcc offset:16
	s_waitcnt vmcnt(16)
	s_cmp_lt_i32 s10, 0
	s_cbranch_scc0 .Ldnc_nz0
	v_mov_b32_e32 v52, 0
	v_mov_b32_e32 v53, 0
	v_mov_b32_e32 v54, 0
	v_mov_b32_e32 v55, 0
	v_mov_b32_e32 v56, 0
	v_mov_b32_e32 v57, 0
	v_mov_b32_e32 v58, 0
	v_mov_b32_e32 v59, 0
	v_mov_b32_e32 v60, 0
	v_mov_b32_e32 v61, 0
	v_mov_b32_e32 v62, 0
	v_mov_b32_e32 v63, 0
; __device__ __forceinline__ unsigned pk2(float lo, float hi) { const f32v2_t v = {lo, hi}; const bf16v2_t b = __builtin_convertvector(v, bf16v2_t); return __builtin_bit_cast(unsigned, b); }
; __device__ __forceinline__ float lo16(unsigned u) { return __uint_as_float(u << 16); }
; __device__ __forceinline__ float hi16(unsigned u) { return __uint_as_float(u & 0xffff0000u); }
; __device__ __forceinline__ float siluf_(float x) { return x * __builtin_amdgcn_rcpf(1.0f + __expf(-x)); }
; __device__ __forceinline__ void prep_dn_finish(const float* cw, bf16_t* dq, bf16_t* dk, bf16_t* dv, const u32x4 (&raw)[4], int t, int ch) {
;     float a[8];
; #pragma unroll
;     for (int e = 0; e < 8; ++e) a[e] = 0.f;
; #pragma unroll
;     for (int k = 0; k < 4; ++k) {
;         const f32x4 w0 = *(const f32x4*)(cw + k * 3072 + ch), w1 = *(const f32x4*)(cw + k * 3072 + ch + 4);
;         a[0] += w0[0] * lo16(raw[k].x); a[1] += w0[1] * hi16(raw[k].x); a[2] += w0[2] * lo16(raw[k].y); a[3] += w0[3] * hi16(raw[k].y);
;         a[4] += w1[0] * lo16(raw[k].z); a[5] += w1[1] * hi16(raw[k].z); a[6] += w1[2] * lo16(raw[k].w); a[7] += w1[3] * hi16(raw[k].w); }
;     float ss = 0.f;
; #pragma unroll
;     for (int e = 0; e < 8; ++e) { a[e] = siluf_(a[e]); ss += a[e] * a[e]; }
;     ss += __shfl_xor(ss, 1); ss += __shfl_xor(ss, 2); ss += __shfl_xor(ss, 4); ss += __shfl_xor(ss, 8);
;     float sc = 1.0f;
;     if (ch < 2048) { sc = rsqrtf(ss + EPS); if (ch < 1024) sc *= 0.08838834764831845f; }
;     u32x4 w; w.x = pk2(a[0] * sc, a[1] * sc); w.y = pk2(a[2] * sc, a[3] * sc); w.z = pk2(a[4] * sc, a[5] * sc); w.w = pk2(a[6] * sc, a[7] * sc);
;     bf16_t* dst = (ch < 1024) ? dq : (ch < 2048 ? dk : dv);
;     *(u32x4*)(dst + (size_t)t * 1024 + (ch & 1023)) = w;
.Ldnc_nz0:
	v_lshlrev_b32_e32 v128, 16, v52
	v_and_b32_e32 v129, 0xffff0000, v52
	v_lshlrev_b32_e32 v130, 16, v53
	v_and_b32_e32 v131, 0xffff0000, v53
	v_lshlrev_b32_e32 v132, 16, v54
	v_and_b32_e32 v133, 0xffff0000, v54
	v_lshlrev_b32_e32 v134, 16, v55
	v_and_b32_e32 v135, 0xffff0000, v55
	v_lshlrev_b32_e32 v136, 16, v56
	v_and_b32_e32 v137, 0xffff0000, v56
	v_lshlrev_b32_e32 v138, 16, v57
	v_and_b32_e32 v139, 0xffff0000, v57
	v_lshlrev_b32_e32 v140, 16, v58
	v_and_b32_e32 v141, 0xffff0000, v58
	v_lshlrev_b32_e32 v142, 16, v59
	v_and_b32_e32 v143, 0xffff0000, v59
	v_lshlrev_b32_e32 v146, 16, v60
	v_and_b32_e32 v147, 0xffff0000, v60
	v_lshlrev_b32_e32 v148, 16, v61
	v_and_b32_e32 v149, 0xffff0000, v61
	v_lshlrev_b32_e32 v150, 16, v62
	v_and_b32_e32 v151, 0xffff0000, v62
	v_lshlrev_b32_e32 v152, 16, v63
	v_and_b32_e32 v153, 0xffff0000, v63
	global_load_dwordx4 v[52:55], v1, s[100:101]
	s_add_u32 s100, s100, 0x7e00
	s_addc_u32 s101, s101, 0
	global_load_dwordx4 v[56:59], v1, s[100:101]
	s_add_u32 s100, s100, 0x7e00
	s_addc_u32 s101, s101, 0
	global_load_dwordx4 v[60:63], v1, s[100:101]
	s_add_u32 s100, s100, 0x7e00
	s_addc_u32 s101, s101, 0
	s_waitcnt vmcnt(18)
	v_lshlrev_b32_e32 v154, 16, v64
	v_and_b32_e32 v155, 0xffff0000, v64
	v_lshlrev_b32_e32 v156, 16, v65
	v_and_b32_e32 v157, 0xffff0000, v65
	v_lshlrev_b32_e32 v158, 16, v66
	v_and_b32_e32 v159, 0xffff0000, v66
	v_lshlrev_b32_e32 v160, 16, v67
	v_and_b32_e32 v161, 0xffff0000, v67
	global_load_dwordx4 v[64:67], v1, s[100:101]
	s_add_u32 s100, s100, 0x7e00
	s_addc_u32 s101, s101, 0
	v_pk_mul_f32 v[162:163], v[96:97], v[128:129]
	v_pk_mul_f32 v[164:165], v[98:99], v[130:131]
	v_pk_mul_f32 v[166:167], v[100:101], v[132:133]
	v_pk_mul_f32 v[168:169], v[102:103], v[134:135]
	v_pk_fma_f32 v[162:163], v[104:105], v[136:137], v[162:163]
	v_pk_fma_f32 v[164:165], v[106:107], v[138:139], v[164:165]
	v_pk_fma_f32 v[166:167], v[108:109], v[140:141], v[166:167]
	v_pk_fma_f32 v[168:169], v[110:111], v[142:143], v[168:169]
	v_pk_fma_f32 v[162:163], v[112:113], v[146:147], v[162:163]
	v_pk_fma_f32 v[164:165], v[114:115], v[148:149], v[164:165]
	v_pk_fma_f32 v[166:167], v[116:117], v[150:151], v[166:167]
	v_pk_fma_f32 v[168:169], v[118:119], v[152:153], v[168:169]
	v_pk_fma_f32 v[162:163], v[120:121], v[154:155], v[162:163]
	v_pk_fma_f32 v[164:165], v[122:123], v[156:157], v[164:165]
	v_pk_fma_f32 v[166:167], v[124:125], v[158:159], v[166:167]
	v_pk_fma_f32 v[168:169], v[126:127], v[160:161], v[168:169]
	v_pk_mul_f32 v[40:41], v[162:163], s[12:13]
	v_pk_mul_f32 v[42:43], v[164:165], s[12:13]
	v_pk_mul_f32 v[44:45], v[166:167], s[12:13]
	v_pk_mul_f32 v[46:47], v[168:169], s[12:13]
	v_exp_f32_e32 v40, v40
	v_exp_f32_e32 v41, v41
	v_exp_f32_e32 v42, v42
	v_exp_f32_e32 v43, v43
	v_exp_f32_e32 v44, v44
	v_exp_f32_e32 v45, v45
	v_exp_f32_e32 v46, v46
	v_exp_f32_e32 v47, v47
	v_pk_add_f32 v[40:41], v[40:41], s[14:15]
	v_pk_add_f32 v[42:43], v[42:43], s[14:15]
	v_pk_add_f32 v[44:45], v[44:45], s[14:15]
	v_pk_add_f32 v[46:47], v[46:47], s[14:15]
	v_rcp_f32_e32 v40, v40
	v_rcp_f32_e32 v41, v41
	v_rcp_f32_e32 v42, v42
	v_rcp_f32_e32 v43, v43
	v_rcp_f32_e32 v44, v44
	v_rcp_f32_e32 v45, v45
	v_rcp_f32_e32 v46, v46
	v_rcp_f32_e32 v47, v47
	v_pk_mul_f32 v[162:163], v[162:163], v[40:41]
	v_pk_mul_f32 v[164:165], v[164:165], v[42:43]
	v_pk_mul_f32 v[166:167], v[166:167], v[44:45]
	v_pk_mul_f32 v[168:169], v[168:169], v[46:47]
	v_pk_mul_f32 v[40:41], v[162:163], v[162:163]
	v_pk_fma_f32 v[40:41], v[164:165], v[164:165], v[40:41]
	v_pk_fma_f32 v[40:41], v[166:167], v[166:167], v[40:41]
	v_pk_fma_f32 v[40:41], v[168:169], v[168:169], v[40:41]
	s_nop 0
	v_add_f32_e32 v50, v40, v41
	s_nop 1
	v_add_f32_dpp v50, v50, v50 quad_perm:[1,0,3,2] row_mask:0xf bank_mask:0xf
	s_nop 1
	v_add_f32_dpp v50, v50, v50 quad_perm:[2,3,0,1] row_mask:0xf bank_mask:0xf
	s_nop 1
	v_add_f32_dpp v50, v50, v50 row_half_mirror row_mask:0xf bank_mask:0xf
	s_nop 1
	v_add_f32_dpp v50, v50, v50 row_mirror row_mask:0xf bank_mask:0xf
	v_add_f32_e32 v50, 0x358637bd, v50
	v_rsq_f32_e32 v50, v50
	s_nop 0
	v_mul_f32_e32 v50, 0x3db504f3, v50
	v_pk_mul_f32 v[162:163], v[162:163], v[50:51] op_sel_hi:[1,0]
	v_pk_mul_f32 v[164:165], v[164:165], v[50:51] op_sel_hi:[1,0]
	v_pk_mul_f32 v[166:167], v[166:167], v[50:51] op_sel_hi:[1,0]
	v_pk_mul_f32 v[168:169], v[168:169], v[50:51] op_sel_hi:[1,0]
	v_cvt_pk_bf16_f32 v170, v162, v163
	v_cvt_pk_bf16_f32 v171, v164, v165
	v_cvt_pk_bf16_f32 v172, v166, v167
	v_cvt_pk_bf16_f32 v173, v168, v169
	global_store_dwordx4 v4, v[170:173], s[6:7]
	s_add_u32 s6, s6, 0x800
	s_addc_u32 s7, s7, 0
	s_waitcnt vmcnt(19)
; __device__ __forceinline__ unsigned pk2(float lo, float hi) { const f32v2_t v = {lo, hi}; const bf16v2_t b = __builtin_convertvector(v, bf16v2_t); return __builtin_bit_cast(unsigned, b); }
; __device__ __forceinline__ float lo16(unsigned u) { return __uint_as_float(u << 16); }
; __device__ __forceinline__ float hi16(unsigned u) { return __uint_as_float(u & 0xffff0000u); }
; __device__ __forceinline__ float siluf_(float x) { return x * __builtin_amdgcn_rcpf(1.0f + __expf(-x)); }
; __device__ __forceinline__ void prep_dn_finish(const float* cw, bf16_t* dq, bf16_t* dk, bf16_t* dv, const u32x4 (&raw)[4], int t, int ch) {
;     float a[8];
; #pragma unroll
;     for (int e = 0; e < 8; ++e) a[e] = 0.f;
; #pragma unroll
;     for (int k = 0; k < 4; ++k) {
;         const f32x4 w0 = *(const f32x4*)(cw + k * 3072 + ch), w1 = *(const f32x4*)(cw + k * 3072 + ch + 4);
;         a[0] += w0[0] * lo16(raw[k].x); a[1] += w0[1] * hi16(raw[k].x); a[2] += w0[2] * lo16(raw[k].y); a[3] += w0[3] * hi16(raw[k].y);
;         a[4] += w1[0] * lo16(raw[k].z); a[5] += w1[1] * hi16(raw[k].z); a[6] += w1[2] * lo16(raw[k].w); a[7] += w1[3] * hi16(raw[k].w); }
;     float ss = 0.f;
; #pragma unroll
;     for (int e = 0; e < 8; ++e) { a[e] = siluf_(a[e]); ss += a[e] * a[e]; }
;     ss += __shfl_xor(ss, 1); ss += __shfl_xor(ss, 2); ss += __shfl_xor(ss, 4); ss += __shfl_xor(ss, 8);
;     float sc = 1.0f;
;     if (ch < 2048) { sc = rsqrtf(ss + EPS); if (ch < 1024) sc *= 0.08838834764831845f; }
;     u32x4 w; w.x = pk2(a[0] * sc, a[1] * sc); w.y = pk2(a[2] * sc, a[3] * sc); w.z = pk2(a[4] * sc, a[5] * sc); w.w = pk2(a[6] * sc, a[7] * sc);
;     bf16_t* dst = (ch < 1024) ? dq : (ch < 2048 ? dk : dv);
;     *(u32x4*)(dst + (size_t)t * 1024 + (ch & 1023)) = w;
	v_lshlrev_b32_e32 v128, 16, v68
	v_and_b32_e32 v129, 0xffff0000, v68
	v_lshlrev_b32_e32 v130, 16, v69
	v_and_b32_e32 v131, 0xffff0000, v69
	v_lshlrev_b32_e32 v132, 16, v70
	v_and_b32_e32 v133, 0xffff0000, v70
	v_lshlrev_b32_e32 v134, 16, v71
	v_and_b32_e32 v135, 0xffff0000, v71
	global_load_dwordx4 v[68:71], v1, s[100:101]
	s_add_u32 s100, s100, 0x7e00
	s_addc_u32 s101, s101, 0
	v_pk_mul_f32 v[162:163], v[96:97], v[136:137]
	v_pk_mul_f32 v[164:165], v[98:99], v[138:139]
	v_pk_mul_f32 v[166:167], v[100:101], v[140:141]
	v_pk_mul_f32 v[168:169], v[102:103], v[142:143]
	v_pk_fma_f32 v[162:163], v[104:105], v[146:147], v[162:163]
	v_pk_fma_f32 v[164:165], v[106:107], v[148:149], v[164:165]
	v_pk_fma_f32 v[166:167], v[108:109], v[150:151], v[166:167]
	v_pk_fma_f32 v[168:169], v[110:111], v[152:153], v[168:169]
	v_pk_fma_f32 v[162:163], v[112:113], v[154:155], v[162:163]
	v_pk_fma_f32 v[164:165], v[114:115], v[156:157], v[164:165]
	v_pk_fma_f32 v[166:167], v[116:117], v[158:159], v[166:167]
	v_pk_fma_f32 v[168:169], v[118:119], v[160:161], v[168:169]
	v_pk_fma_f32 v[162:163], v[120:121], v[128:129], v[162:163]
	v_pk_fma_f32 v[164:165], v[122:123], v[130:131], v[164:165]
	v_pk_fma_f32 v[166:167], v[124:125], v[132:133], v[166:167]
	v_pk_fma_f32 v[168:169], v[126:127], v[134:135], v[168:169]
	v_pk_mul_f32 v[40:41], v[162:163], s[12:13]
	v_pk_mul_f32 v[42:43], v[164:165], s[12:13]
	v_pk_mul_f32 v[44:45], v[166:167], s[12:13]
	v_pk_mul_f32 v[46:47], v[168:169], s[12:13]
	v_exp_f32_e32 v40, v40
	v_exp_f32_e32 v41, v41
	v_exp_f32_e32 v42, v42
	v_exp_f32_e32 v43, v43
	v_exp_f32_e32 v44, v44
	v_exp_f32_e32 v45, v45
	v_exp_f32_e32 v46, v46
	v_exp_f32_e32 v47, v47
	v_pk_add_f32 v[40:41], v[40:41], s[14:15]
	v_pk_add_f32 v[42:43], v[42:43], s[14:15]
	v_pk_add_f32 v[44:45], v[44:45], s[14:15]
	v_pk_add_f32 v[46:47], v[46:47], s[14:15]
	v_rcp_f32_e32 v40, v40
	v_rcp_f32_e32 v41, v41
	v_rcp_f32_e32 v42, v42
	v_rcp_f32_e32 v43, v43
	v_rcp_f32_e32 v44, v44
	v_rcp_f32_e32 v45, v45
	v_rcp_f32_e32 v46, v46
	v_rcp_f32_e32 v47, v47
	v_pk_mul_f32 v[162:163], v[162:163], v[40:41]
	v_pk_mul_f32 v[164:165], v[164:165], v[42:43]
	v_pk_mul_f32 v[166:167], v[166:167], v[44:45]
	v_pk_mul_f32 v[168:169], v[168:169], v[46:47]
	v_pk_mul_f32 v[40:41], v[162:163], v[162:163]
	v_pk_fma_f32 v[40:41], v[164:165], v[164:165], v[40:41]
	v_pk_fma_f32 v[40:41], v[166:167], v[166:167], v[40:41]
	v_pk_fma_f32 v[40:41], v[168:169], v[168:169], v[40:41]
	s_nop 0
	v_add_f32_e32 v50, v40, v41
	s_nop 1
	v_add_f32_dpp v50, v50, v50 quad_perm:[1,0,3,2] row_mask:0xf bank_mask:0xf
	s_nop 1
	v_add_f32_dpp v50, v50, v50 quad_perm:[2,3,0,1] row_mask:0xf bank_mask:0xf
	s_nop 1
	v_add_f32_dpp v50, v50, v50 row_half_mirror row_mask:0xf bank_mask:0xf
	s_nop 1
	v_add_f32_dpp v50, v50, v50 row_mirror row_mask:0xf bank_mask:0xf
	v_add_f32_e32 v50, 0x358637bd, v50
	v_rsq_f32_e32 v50, v50
	s_nop 0
	v_mul_f32_e32 v50, 0x3db504f3, v50
	v_pk_mul_f32 v[162:163], v[162:163], v[50:51] op_sel_hi:[1,0]
	v_pk_mul_f32 v[164:165], v[164:165], v[50:51] op_sel_hi:[1,0]
	v_pk_mul_f32 v[166:167], v[166:167], v[50:51] op_sel_hi:[1,0]
	v_pk_mul_f32 v[168:169], v[168:169], v[50:51] op_sel_hi:[1,0]
	v_cvt_pk_bf16_f32 v170, v162, v163
	v_cvt_pk_bf16_f32 v171, v164, v165
	v_cvt_pk_bf16_f32 v172, v166, v167
	v_cvt_pk_bf16_f32 v173, v168, v169
	global_store_dwordx4 v4, v[170:173], s[6:7]
	s_add_u32 s6, s6, 0x800
	s_addc_u32 s7, s7, 0
	s_waitcnt vmcnt(20)
	v_lshlrev_b32_e32 v136, 16, v72
	v_and_b32_e32 v137, 0xffff0000, v72
	v_lshlrev_b32_e32 v138, 16, v73
	v_and_b32_e32 v139, 0xffff0000, v73
	v_lshlrev_b32_e32 v140, 16, v74
	v_and_b32_e32 v141, 0xffff0000, v74
	v_lshlrev_b32_e32 v142, 16, v75
	v_and_b32_e32 v143, 0xffff0000, v75
	global_load_dwordx4 v[72:75], v1, s[100:101]
	s_add_u32 s100, s100, 0x7e00
	s_addc_u32 s101, s101, 0
	v_pk_mul_f32 v[162:163], v[96:97], v[146:147]
	v_pk_mul_f32 v[164:165], v[98:99], v[148:149]
	v_pk_mul_f32 v[166:167], v[100:101], v[150:151]
	v_pk_mul_f32 v[168:169], v[102:103], v[152:153]
	v_pk_fma_f32 v[162:163], v[104:105], v[154:155], v[162:163]
	v_pk_fma_f32 v[164:165], v[106:107], v[156:157], v[164:165]
	v_pk_fma_f32 v[166:167], v[108:109], v[158:159], v[166:167]
	v_pk_fma_f32 v[168:169], v[110:111], v[160:161], v[168:169]
	v_pk_fma_f32 v[162:163], v[112:113], v[128:129], v[162:163]
	v_pk_fma_f32 v[164:165], v[114:115], v[130:131], v[164:165]
	v_pk_fma_f32 v[166:167], v[116:117], v[132:133], v[166:167]
	v_pk_fma_f32 v[168:169], v[118:119], v[134:135], v[168:169]
	v_pk_fma_f32 v[162:163], v[120:121], v[136:137], v[162:163]
	v_pk_fma_f32 v[164:165], v[122:123], v[138:139], v[164:165]
	v_pk_fma_f32 v[166:167], v[124:125], v[140:141], v[166:167]
	v_pk_fma_f32 v[168:169], v[126:127], v[142:143], v[168:169]
	v_pk_mul_f32 v[40:41], v[162:163], s[12:13]
	v_pk_mul_f32 v[42:43], v[164:165], s[12:13]
	v_pk_mul_f32 v[44:45], v[166:167], s[12:13]
	v_pk_mul_f32 v[46:47], v[168:169], s[12:13]
	v_exp_f32_e32 v40, v40
	v_exp_f32_e32 v41, v41
	v_exp_f32_e32 v42, v42
	v_exp_f32_e32 v43, v43
	v_exp_f32_e32 v44, v44
	v_exp_f32_e32 v45, v45
	v_exp_f32_e32 v46, v46
	v_exp_f32_e32 v47, v47
	v_pk_add_f32 v[40:41], v[40:41], s[14:15]
	v_pk_add_f32 v[42:43], v[42:43], s[14:15]
	v_pk_add_f32 v[44:45], v[44:45], s[14:15]
	v_pk_add_f32 v[46:47], v[46:47], s[14:15]
	v_rcp_f32_e32 v40, v40
	v_rcp_f32_e32 v41, v41
	v_rcp_f32_e32 v42, v42
	v_rcp_f32_e32 v43, v43
	v_rcp_f32_e32 v44, v44
	v_rcp_f32_e32 v45, v45
	v_rcp_f32_e32 v46, v46
	v_rcp_f32_e32 v47, v47
	v_pk_mul_f32 v[162:163], v[162:163], v[40:41]
	v_pk_mul_f32 v[164:165], v[164:165], v[42:43]
	v_pk_mul_f32 v[166:167], v[166:167], v[44:45]
	v_pk_mul_f32 v[168:169], v[168:169], v[46:47]
	v_pk_mul_f32 v[40:41], v[162:163], v[162:163]
	v_pk_fma_f32 v[40:41], v[164:165], v[164:165], v[40:41]
	v_pk_fma_f32 v[40:41], v[166:167], v[166:167], v[40:41]
	v_pk_fma_f32 v[40:41], v[168:169], v[168:169], v[40:41]
	s_nop 0
	v_add_f32_e32 v50, v40, v41
	s_nop 1
	v_add_f32_dpp v50, v50, v50 quad_perm:[1,0,3,2] row_mask:0xf bank_mask:0xf
	s_nop 1
	v_add_f32_dpp v50, v50, v50 quad_perm:[2,3,0,1] row_mask:0xf bank_mask:0xf
	s_nop 1
	v_add_f32_dpp v50, v50, v50 row_half_mirror row_mask:0xf bank_mask:0xf
	s_nop 1
	v_add_f32_dpp v50, v50, v50 row_mirror row_mask:0xf bank_mask:0xf
	v_add_f32_e32 v50, 0x358637bd, v50
	v_rsq_f32_e32 v50, v50
	s_nop 0
	v_mul_f32_e32 v50, 0x3db504f3, v50
	v_pk_mul_f32 v[162:163], v[162:163], v[50:51] op_sel_hi:[1,0]
	v_pk_mul_f32 v[164:165], v[164:165], v[50:51] op_sel_hi:[1,0]
	v_pk_mul_f32 v[166:167], v[166:167], v[50:51] op_sel_hi:[1,0]
	v_pk_mul_f32 v[168:169], v[168:169], v[50:51] op_sel_hi:[1,0]
	v_cvt_pk_bf16_f32 v170, v162, v163
	v_cvt_pk_bf16_f32 v171, v164, v165
	v_cvt_pk_bf16_f32 v172, v166, v167
	v_cvt_pk_bf16_f32 v173, v168, v169
	global_store_dwordx4 v4, v[170:173], s[6:7]
	s_add_u32 s6, s6, 0x800
	s_addc_u32 s7, s7, 0
	s_waitcnt vmcnt(21)
; __device__ __forceinline__ unsigned pk2(float lo, float hi) { const f32v2_t v = {lo, hi}; const bf16v2_t b = __builtin_convertvector(v, bf16v2_t); return __builtin_bit_cast(unsigned, b); }
; __device__ __forceinline__ float lo16(unsigned u) { return __uint_as_float(u << 16); }
; __device__ __forceinline__ float hi16(unsigned u) { return __uint_as_float(u & 0xffff0000u); }
; __device__ __forceinline__ float siluf_(float x) { return x * __builtin_amdgcn_rcpf(1.0f + __expf(-x)); }
; __device__ __forceinline__ void prep_dn_finish(const float* cw, bf16_t* dq, bf16_t* dk, bf16_t* dv, const u32x4 (&raw)[4], int t, int ch) {
;     float a[8];
; #pragma unroll
;     for (int e = 0; e < 8; ++e) a[e] = 0.f;
; #pragma unroll
;     for (int k = 0; k < 4; ++k) {
;         const f32x4 w0 = *(const f32x4*)(cw + k * 3072 + ch), w1 = *(const f32x4*)(cw + k * 3072 + ch + 4);
;         a[0] += w0[0] * lo16(raw[k].x); a[1] += w0[1] * hi16(raw[k].x); a[2] += w0[2] * lo16(raw[k].y); a[3] += w0[3] * hi16(raw[k].y);
;         a[4] += w1[0] * lo16(raw[k].z); a[5] += w1[1] * hi16(raw[k].z); a[6] += w1[2] * lo16(raw[k].w); a[7] += w1[3] * hi16(raw[k].w); }
;     float ss = 0.f;
; #pragma unroll
;     for (int e = 0; e < 8; ++e) { a[e] = siluf_(a[e]); ss += a[e] * a[e]; }
;     ss += __shfl_xor(ss, 1); ss += __shfl_xor(ss, 2); ss += __shfl_xor(ss, 4); ss += __shfl_xor(ss, 8);
;     float sc = 1.0f;
;     if (ch < 2048) { sc = rsqrtf(ss + EPS); if (ch < 1024) sc *= 0.08838834764831845f; }
;     u32x4 w; w.x = pk2(a[0] * sc, a[1] * sc); w.y = pk2(a[2] * sc, a[3] * sc); w.z = pk2(a[4] * sc, a[5] * sc); w.w = pk2(a[6] * sc, a[7] * sc);
;     bf16_t* dst = (ch < 1024) ? dq : (ch < 2048 ? dk : dv);
;     *(u32x4*)(dst + (size_t)t * 1024 + (ch & 1023)) = w;
	v_lshlrev_b32_e32 v146, 16, v76
	v_and_b32_e32 v147, 0xffff0000, v76
	v_lshlrev_b32_e32 v148, 16, v77
	v_and_b32_e32 v149, 0xffff0000, v77
	v_lshlrev_b32_e32 v150, 16, v78
	v_and_b32_e32 v151, 0xffff0000, v78
	v_lshlrev_b32_e32 v152, 16, v79
	v_and_b32_e32 v153, 0xffff0000, v79
	global_load_dwordx4 v[76:79], v1, s[100:101]
	s_add_u32 s100, s100, 0x7e00
	s_addc_u32 s101, s101, 0
	v_pk_mul_f32 v[162:163], v[96:97], v[154:155]
	v_pk_mul_f32 v[164:165], v[98:99], v[156:157]
	v_pk_mul_f32 v[166:167], v[100:101], v[158:159]
	v_pk_mul_f32 v[168:169], v[102:103], v[160:161]
	v_pk_fma_f32 v[162:163], v[104:105], v[128:129], v[162:163]
	v_pk_fma_f32 v[164:165], v[106:107], v[130:131], v[164:165]
	v_pk_fma_f32 v[166:167], v[108:109], v[132:133], v[166:167]
	v_pk_fma_f32 v[168:169], v[110:111], v[134:135], v[168:169]
	v_pk_fma_f32 v[162:163], v[112:113], v[136:137], v[162:163]
	v_pk_fma_f32 v[164:165], v[114:115], v[138:139], v[164:165]
	v_pk_fma_f32 v[166:167], v[116:117], v[140:141], v[166:167]
	v_pk_fma_f32 v[168:169], v[118:119], v[142:143], v[168:169]
	v_pk_fma_f32 v[162:163], v[120:121], v[146:147], v[162:163]
	v_pk_fma_f32 v[164:165], v[122:123], v[148:149], v[164:165]
	v_pk_fma_f32 v[166:167], v[124:125], v[150:151], v[166:167]
	v_pk_fma_f32 v[168:169], v[126:127], v[152:153], v[168:169]
	v_pk_mul_f32 v[40:41], v[162:163], s[12:13]
	v_pk_mul_f32 v[42:43], v[164:165], s[12:13]
	v_pk_mul_f32 v[44:45], v[166:167], s[12:13]
	v_pk_mul_f32 v[46:47], v[168:169], s[12:13]
	v_exp_f32_e32 v40, v40
	v_exp_f32_e32 v41, v41
	v_exp_f32_e32 v42, v42
	v_exp_f32_e32 v43, v43
	v_exp_f32_e32 v44, v44
	v_exp_f32_e32 v45, v45
	v_exp_f32_e32 v46, v46
	v_exp_f32_e32 v47, v47
	v_pk_add_f32 v[40:41], v[40:41], s[14:15]
	v_pk_add_f32 v[42:43], v[42:43], s[14:15]
	v_pk_add_f32 v[44:45], v[44:45], s[14:15]
	v_pk_add_f32 v[46:47], v[46:47], s[14:15]
	v_rcp_f32_e32 v40, v40
	v_rcp_f32_e32 v41, v41
	v_rcp_f32_e32 v42, v42
	v_rcp_f32_e32 v43, v43
	v_rcp_f32_e32 v44, v44
	v_rcp_f32_e32 v45, v45
	v_rcp_f32_e32 v46, v46
	v_rcp_f32_e32 v47, v47
	v_pk_mul_f32 v[162:163], v[162:163], v[40:41]
	v_pk_mul_f32 v[164:165], v[164:165], v[42:43]
	v_pk_mul_f32 v[166:167], v[166:167], v[44:45]
	v_pk_mul_f32 v[168:169], v[168:169], v[46:47]
	v_pk_mul_f32 v[40:41], v[162:163], v[162:163]
	v_pk_fma_f32 v[40:41], v[164:165], v[164:165], v[40:41]
	v_pk_fma_f32 v[40:41], v[166:167], v[166:167], v[40:41]
	v_pk_fma_f32 v[40:41], v[168:169], v[168:169], v[40:41]
	s_nop 0
	v_add_f32_e32 v50, v40, v41
	s_nop 1
	v_add_f32_dpp v50, v50, v50 quad_perm:[1,0,3,2] row_mask:0xf bank_mask:0xf
	s_nop 1
	v_add_f32_dpp v50, v50, v50 quad_perm:[2,3,0,1] row_mask:0xf bank_mask:0xf
	s_nop 1
	v_add_f32_dpp v50, v50, v50 row_half_mirror row_mask:0xf bank_mask:0xf
	s_nop 1
	v_add_f32_dpp v50, v50, v50 row_mirror row_mask:0xf bank_mask:0xf
	v_add_f32_e32 v50, 0x358637bd, v50
	v_rsq_f32_e32 v50, v50
	s_nop 0
	v_mul_f32_e32 v50, 0x3db504f3, v50
	v_pk_mul_f32 v[162:163], v[162:163], v[50:51] op_sel_hi:[1,0]
	v_pk_mul_f32 v[164:165], v[164:165], v[50:51] op_sel_hi:[1,0]
	v_pk_mul_f32 v[166:167], v[166:167], v[50:51] op_sel_hi:[1,0]
	v_pk_mul_f32 v[168:169], v[168:169], v[50:51] op_sel_hi:[1,0]
	v_cvt_pk_bf16_f32 v170, v162, v163
	v_cvt_pk_bf16_f32 v171, v164, v165
	v_cvt_pk_bf16_f32 v172, v166, v167
	v_cvt_pk_bf16_f32 v173, v168, v169
	global_store_dwordx4 v4, v[170:173], s[6:7]
	s_add_u32 s6, s6, 0x800
	s_addc_u32 s7, s7, 0
	s_waitcnt vmcnt(22)
	v_lshlrev_b32_e32 v154, 16, v80
	v_and_b32_e32 v155, 0xffff0000, v80
	v_lshlrev_b32_e32 v156, 16, v81
	v_and_b32_e32 v157, 0xffff0000, v81
	v_lshlrev_b32_e32 v158, 16, v82
	v_and_b32_e32 v159, 0xffff0000, v82
	v_lshlrev_b32_e32 v160, 16, v83
	v_and_b32_e32 v161, 0xffff0000, v83
	global_load_dwordx4 v[80:83], v1, s[100:101]
	s_add_u32 s100, s100, 0x7e00
	s_addc_u32 s101, s101, 0
	v_pk_mul_f32 v[162:163], v[96:97], v[128:129]
	v_pk_mul_f32 v[164:165], v[98:99], v[130:131]
	v_pk_mul_f32 v[166:167], v[100:101], v[132:133]
	v_pk_mul_f32 v[168:169], v[102:103], v[134:135]
	v_pk_fma_f32 v[162:163], v[104:105], v[136:137], v[162:163]
	v_pk_fma_f32 v[164:165], v[106:107], v[138:139], v[164:165]
	v_pk_fma_f32 v[166:167], v[108:109], v[140:141], v[166:167]
	v_pk_fma_f32 v[168:169], v[110:111], v[142:143], v[168:169]
	v_pk_fma_f32 v[162:163], v[112:113], v[146:147], v[162:163]
	v_pk_fma_f32 v[164:165], v[114:115], v[148:149], v[164:165]
	v_pk_fma_f32 v[166:167], v[116:117], v[150:151], v[166:167]
	v_pk_fma_f32 v[168:169], v[118:119], v[152:153], v[168:169]
	v_pk_fma_f32 v[162:163], v[120:121], v[154:155], v[162:163]
	v_pk_fma_f32 v[164:165], v[122:123], v[156:157], v[164:165]
	v_pk_fma_f32 v[166:167], v[124:125], v[158:159], v[166:167]
	v_pk_fma_f32 v[168:169], v[126:127], v[160:161], v[168:169]
	v_pk_mul_f32 v[40:41], v[162:163], s[12:13]
	v_pk_mul_f32 v[42:43], v[164:165], s[12:13]
	v_pk_mul_f32 v[44:45], v[166:167], s[12:13]
	v_pk_mul_f32 v[46:47], v[168:169], s[12:13]
	v_exp_f32_e32 v40, v40
	v_exp_f32_e32 v41, v41
	v_exp_f32_e32 v42, v42
	v_exp_f32_e32 v43, v43
	v_exp_f32_e32 v44, v44
	v_exp_f32_e32 v45, v45
	v_exp_f32_e32 v46, v46
	v_exp_f32_e32 v47, v47
	v_pk_add_f32 v[40:41], v[40:41], s[14:15]
	v_pk_add_f32 v[42:43], v[42:43], s[14:15]
	v_pk_add_f32 v[44:45], v[44:45], s[14:15]
	v_pk_add_f32 v[46:47], v[46:47], s[14:15]
	v_rcp_f32_e32 v40, v40
	v_rcp_f32_e32 v41, v41
	v_rcp_f32_e32 v42, v42
	v_rcp_f32_e32 v43, v43
	v_rcp_f32_e32 v44, v44
	v_rcp_f32_e32 v45, v45
	v_rcp_f32_e32 v46, v46
	v_rcp_f32_e32 v47, v47
	v_pk_mul_f32 v[162:163], v[162:163], v[40:41]
	v_pk_mul_f32 v[164:165], v[164:165], v[42:43]
	v_pk_mul_f32 v[166:167], v[166:167], v[44:45]
	v_pk_mul_f32 v[168:169], v[168:169], v[46:47]
	v_pk_mul_f32 v[40:41], v[162:163], v[162:163]
	v_pk_fma_f32 v[40:41], v[164:165], v[164:165], v[40:41]
	v_pk_fma_f32 v[40:41], v[166:167], v[166:167], v[40:41]
	v_pk_fma_f32 v[40:41], v[168:169], v[168:169], v[40:41]
	s_nop 0
	v_add_f32_e32 v50, v40, v41
	s_nop 1
	v_add_f32_dpp v50, v50, v50 quad_perm:[1,0,3,2] row_mask:0xf bank_mask:0xf
	s_nop 1
	v_add_f32_dpp v50, v50, v50 quad_perm:[2,3,0,1] row_mask:0xf bank_mask:0xf
	s_nop 1
	v_add_f32_dpp v50, v50, v50 row_half_mirror row_mask:0xf bank_mask:0xf
	s_nop 1
	v_add_f32_dpp v50, v50, v50 row_mirror row_mask:0xf bank_mask:0xf
	v_add_f32_e32 v50, 0x358637bd, v50
	v_rsq_f32_e32 v50, v50
	s_nop 0
	v_mul_f32_e32 v50, 0x3db504f3, v50
	v_pk_mul_f32 v[162:163], v[162:163], v[50:51] op_sel_hi:[1,0]
	v_pk_mul_f32 v[164:165], v[164:165], v[50:51] op_sel_hi:[1,0]
	v_pk_mul_f32 v[166:167], v[166:167], v[50:51] op_sel_hi:[1,0]
	v_pk_mul_f32 v[168:169], v[168:169], v[50:51] op_sel_hi:[1,0]
	v_cvt_pk_bf16_f32 v170, v162, v163
	v_cvt_pk_bf16_f32 v171, v164, v165
	v_cvt_pk_bf16_f32 v172, v166, v167
	v_cvt_pk_bf16_f32 v173, v168, v169
	global_store_dwordx4 v4, v[170:173], s[6:7]
	s_add_u32 s6, s6, 0x800
	s_addc_u32 s7, s7, 0
	s_waitcnt vmcnt(23)
; __device__ __forceinline__ unsigned pk2(float lo, float hi) { const f32v2_t v = {lo, hi}; const bf16v2_t b = __builtin_convertvector(v, bf16v2_t); return __builtin_bit_cast(unsigned, b); }
; __device__ __forceinline__ float lo16(unsigned u) { return __uint_as_float(u << 16); }
; __device__ __forceinline__ float hi16(unsigned u) { return __uint_as_float(u & 0xffff0000u); }
; __device__ __forceinline__ float siluf_(float x) { return x * __builtin_amdgcn_rcpf(1.0f + __expf(-x)); }
; __device__ __forceinline__ void prep_dn_finish(const float* cw, bf16_t* dq, bf16_t* dk, bf16_t* dv, const u32x4 (&raw)[4], int t, int ch) {
;     float a[8];
; #pragma unroll
;     for (int e = 0; e < 8; ++e) a[e] = 0.f;
; #pragma unroll
;     for (int k = 0; k < 4; ++k) {
;         const f32x4 w0 = *(const f32x4*)(cw + k * 3072 + ch), w1 = *(const f32x4*)(cw + k * 3072 + ch + 4);
;         a[0] += w0[0] * lo16(raw[k].x); a[1] += w0[1] * hi16(raw[k].x); a[2] += w0[2] * lo16(raw[k].y); a[3] += w0[3] * hi16(raw[k].y);
;         a[4] += w1[0] * lo16(raw[k].z); a[5] += w1[1] * hi16(raw[k].z); a[6] += w1[2] * lo16(raw[k].w); a[7] += w1[3] * hi16(raw[k].w); }
;     float ss = 0.f;
; #pragma unroll
;     for (int e = 0; e < 8; ++e) { a[e] = siluf_(a[e]); ss += a[e] * a[e]; }
;     ss += __shfl_xor(ss, 1); ss += __shfl_xor(ss, 2); ss += __shfl_xor(ss, 4); ss += __shfl_xor(ss, 8);
;     float sc = 1.0f;
;     if (ch < 2048) { sc = rsqrtf(ss + EPS); if (ch < 1024) sc *= 0.08838834764831845f; }
;     u32x4 w; w.x = pk2(a[0] * sc, a[1] * sc); w.y = pk2(a[2] * sc, a[3] * sc); w.z = pk2(a[4] * sc, a[5] * sc); w.w = pk2(a[6] * sc, a[7] * sc);
;     bf16_t* dst = (ch < 1024) ? dq : (ch < 2048 ? dk : dv);
;     *(u32x4*)(dst + (size_t)t * 1024 + (ch & 1023)) = w;
	v_lshlrev_b32_e32 v128, 16, v84
	v_and_b32_e32 v129, 0xffff0000, v84
	v_lshlrev_b32_e32 v130, 16, v85
	v_and_b32_e32 v131, 0xffff0000, v85
	v_lshlrev_b32_e32 v132, 16, v86
	v_and_b32_e32 v133, 0xffff0000, v86
	v_lshlrev_b32_e32 v134, 16, v87
	v_and_b32_e32 v135, 0xffff0000, v87
	global_load_dwordx4 v[84:87], v1, s[100:101]
	s_add_u32 s100, s100, 0x7e00
	s_addc_u32 s101, s101, 0
	v_pk_mul_f32 v[162:163], v[96:97], v[136:137]
	v_pk_mul_f32 v[164:165], v[98:99], v[138:139]
	v_pk_mul_f32 v[166:167], v[100:101], v[140:141]
	v_pk_mul_f32 v[168:169], v[102:103], v[142:143]
	v_pk_fma_f32 v[162:163], v[104:105], v[146:147], v[162:163]
	v_pk_fma_f32 v[164:165], v[106:107], v[148:149], v[164:165]
	v_pk_fma_f32 v[166:167], v[108:109], v[150:151], v[166:167]
	v_pk_fma_f32 v[168:169], v[110:111], v[152:153], v[168:169]
	v_pk_fma_f32 v[162:163], v[112:113], v[154:155], v[162:163]
	v_pk_fma_f32 v[164:165], v[114:115], v[156:157], v[164:165]
	v_pk_fma_f32 v[166:167], v[116:117], v[158:159], v[166:167]
	v_pk_fma_f32 v[168:169], v[118:119], v[160:161], v[168:169]
	v_pk_fma_f32 v[162:163], v[120:121], v[128:129], v[162:163]
	v_pk_fma_f32 v[164:165], v[122:123], v[130:131], v[164:165]
	v_pk_fma_f32 v[166:167], v[124:125], v[132:133], v[166:167]
	v_pk_fma_f32 v[168:169], v[126:127], v[134:135], v[168:169]
	v_pk_mul_f32 v[40:41], v[162:163], s[12:13]
	v_pk_mul_f32 v[42:43], v[164:165], s[12:13]
	v_pk_mul_f32 v[44:45], v[166:167], s[12:13]
	v_pk_mul_f32 v[46:47], v[168:169], s[12:13]
	v_exp_f32_e32 v40, v40
	v_exp_f32_e32 v41, v41
	v_exp_f32_e32 v42, v42
	v_exp_f32_e32 v43, v43
	v_exp_f32_e32 v44, v44
	v_exp_f32_e32 v45, v45
	v_exp_f32_e32 v46, v46
	v_exp_f32_e32 v47, v47
	v_pk_add_f32 v[40:41], v[40:41], s[14:15]
	v_pk_add_f32 v[42:43], v[42:43], s[14:15]
	v_pk_add_f32 v[44:45], v[44:45], s[14:15]
	v_pk_add_f32 v[46:47], v[46:47], s[14:15]
	v_rcp_f32_e32 v40, v40
	v_rcp_f32_e32 v41, v41
	v_rcp_f32_e32 v42, v42
	v_rcp_f32_e32 v43, v43
	v_rcp_f32_e32 v44, v44
	v_rcp_f32_e32 v45, v45
	v_rcp_f32_e32 v46, v46
	v_rcp_f32_e32 v47, v47
	v_pk_mul_f32 v[162:163], v[162:163], v[40:41]
	v_pk_mul_f32 v[164:165], v[164:165], v[42:43]
	v_pk_mul_f32 v[166:167], v[166:167], v[44:45]
	v_pk_mul_f32 v[168:169], v[168:169], v[46:47]
	v_pk_mul_f32 v[40:41], v[162:163], v[162:163]
	v_pk_fma_f32 v[40:41], v[164:165], v[164:165], v[40:41]
	v_pk_fma_f32 v[40:41], v[166:167], v[166:167], v[40:41]
	v_pk_fma_f32 v[40:41], v[168:169], v[168:169], v[40:41]
	s_nop 0
	v_add_f32_e32 v50, v40, v41
	s_nop 1
	v_add_f32_dpp v50, v50, v50 quad_perm:[1,0,3,2] row_mask:0xf bank_mask:0xf
	s_nop 1
	v_add_f32_dpp v50, v50, v50 quad_perm:[2,3,0,1] row_mask:0xf bank_mask:0xf
	s_nop 1
	v_add_f32_dpp v50, v50, v50 row_half_mirror row_mask:0xf bank_mask:0xf
	s_nop 1
	v_add_f32_dpp v50, v50, v50 row_mirror row_mask:0xf bank_mask:0xf
	v_add_f32_e32 v50, 0x358637bd, v50
	v_rsq_f32_e32 v50, v50
	s_nop 0
	v_mul_f32_e32 v50, 0x3db504f3, v50
	v_pk_mul_f32 v[162:163], v[162:163], v[50:51] op_sel_hi:[1,0]
	v_pk_mul_f32 v[164:165], v[164:165], v[50:51] op_sel_hi:[1,0]
	v_pk_mul_f32 v[166:167], v[166:167], v[50:51] op_sel_hi:[1,0]
	v_pk_mul_f32 v[168:169], v[168:169], v[50:51] op_sel_hi:[1,0]
	v_cvt_pk_bf16_f32 v170, v162, v163
	v_cvt_pk_bf16_f32 v171, v164, v165
	v_cvt_pk_bf16_f32 v172, v166, v167
	v_cvt_pk_bf16_f32 v173, v168, v169
	global_store_dwordx4 v4, v[170:173], s[6:7]
	s_add_u32 s6, s6, 0x800
	s_addc_u32 s7, s7, 0
	s_waitcnt vmcnt(24)
	v_lshlrev_b32_e32 v136, 16, v88
	v_and_b32_e32 v137, 0xffff0000, v88
	v_lshlrev_b32_e32 v138, 16, v89
	v_and_b32_e32 v139, 0xffff0000, v89
	v_lshlrev_b32_e32 v140, 16, v90
	v_and_b32_e32 v141, 0xffff0000, v90
	v_lshlrev_b32_e32 v142, 16, v91
	v_and_b32_e32 v143, 0xffff0000, v91
	global_load_dwordx4 v[88:91], v1, s[100:101]
	s_add_u32 s100, s100, 0x7e00
	s_addc_u32 s101, s101, 0
	v_pk_mul_f32 v[162:163], v[96:97], v[146:147]
	v_pk_mul_f32 v[164:165], v[98:99], v[148:149]
	v_pk_mul_f32 v[166:167], v[100:101], v[150:151]
	v_pk_mul_f32 v[168:169], v[102:103], v[152:153]
	v_pk_fma_f32 v[162:163], v[104:105], v[154:155], v[162:163]
	v_pk_fma_f32 v[164:165], v[106:107], v[156:157], v[164:165]
	v_pk_fma_f32 v[166:167], v[108:109], v[158:159], v[166:167]
	v_pk_fma_f32 v[168:169], v[110:111], v[160:161], v[168:169]
	v_pk_fma_f32 v[162:163], v[112:113], v[128:129], v[162:163]
	v_pk_fma_f32 v[164:165], v[114:115], v[130:131], v[164:165]
	v_pk_fma_f32 v[166:167], v[116:117], v[132:133], v[166:167]
	v_pk_fma_f32 v[168:169], v[118:119], v[134:135], v[168:169]
	v_pk_fma_f32 v[162:163], v[120:121], v[136:137], v[162:163]
	v_pk_fma_f32 v[164:165], v[122:123], v[138:139], v[164:165]
	v_pk_fma_f32 v[166:167], v[124:125], v[140:141], v[166:167]
	v_pk_fma_f32 v[168:169], v[126:127], v[142:143], v[168:169]
	v_pk_mul_f32 v[40:41], v[162:163], s[12:13]
	v_pk_mul_f32 v[42:43], v[164:165], s[12:13]
	v_pk_mul_f32 v[44:45], v[166:167], s[12:13]
	v_pk_mul_f32 v[46:47], v[168:169], s[12:13]
	v_exp_f32_e32 v40, v40
	v_exp_f32_e32 v41, v41
	v_exp_f32_e32 v42, v42
	v_exp_f32_e32 v43, v43
	v_exp_f32_e32 v44, v44
	v_exp_f32_e32 v45, v45
	v_exp_f32_e32 v46, v46
	v_exp_f32_e32 v47, v47
	v_pk_add_f32 v[40:41], v[40:41], s[14:15]
	v_pk_add_f32 v[42:43], v[42:43], s[14:15]
	v_pk_add_f32 v[44:45], v[44:45], s[14:15]
	v_pk_add_f32 v[46:47], v[46:47], s[14:15]
	v_rcp_f32_e32 v40, v40
	v_rcp_f32_e32 v41, v41
	v_rcp_f32_e32 v42, v42
	v_rcp_f32_e32 v43, v43
	v_rcp_f32_e32 v44, v44
	v_rcp_f32_e32 v45, v45
	v_rcp_f32_e32 v46, v46
	v_rcp_f32_e32 v47, v47
	v_pk_mul_f32 v[162:163], v[162:163], v[40:41]
	v_pk_mul_f32 v[164:165], v[164:165], v[42:43]
	v_pk_mul_f32 v[166:167], v[166:167], v[44:45]
	v_pk_mul_f32 v[168:169], v[168:169], v[46:47]
	v_pk_mul_f32 v[40:41], v[162:163], v[162:163]
	v_pk_fma_f32 v[40:41], v[164:165], v[164:165], v[40:41]
	v_pk_fma_f32 v[40:41], v[166:167], v[166:167], v[40:41]
	v_pk_fma_f32 v[40:41], v[168:169], v[168:169], v[40:41]
	s_nop 0
	v_add_f32_e32 v50, v40, v41
	s_nop 1
	v_add_f32_dpp v50, v50, v50 quad_perm:[1,0,3,2] row_mask:0xf bank_mask:0xf
	s_nop 1
	v_add_f32_dpp v50, v50, v50 quad_perm:[2,3,0,1] row_mask:0xf bank_mask:0xf
	s_nop 1
	v_add_f32_dpp v50, v50, v50 row_half_mirror row_mask:0xf bank_mask:0xf
	s_nop 1
	v_add_f32_dpp v50, v50, v50 row_mirror row_mask:0xf bank_mask:0xf
	v_add_f32_e32 v50, 0x358637bd, v50
	v_rsq_f32_e32 v50, v50
	s_nop 0
	v_mul_f32_e32 v50, 0x3db504f3, v50
	v_pk_mul_f32 v[162:163], v[162:163], v[50:51] op_sel_hi:[1,0]
	v_pk_mul_f32 v[164:165], v[164:165], v[50:51] op_sel_hi:[1,0]
	v_pk_mul_f32 v[166:167], v[166:167], v[50:51] op_sel_hi:[1,0]
	v_pk_mul_f32 v[168:169], v[168:169], v[50:51] op_sel_hi:[1,0]
	v_cvt_pk_bf16_f32 v170, v162, v163
	v_cvt_pk_bf16_f32 v171, v164, v165
	v_cvt_pk_bf16_f32 v172, v166, v167
	v_cvt_pk_bf16_f32 v173, v168, v169
	global_store_dwordx4 v4, v[170:173], s[6:7]
	s_add_u32 s6, s6, 0x800
	s_addc_u32 s7, s7, 0
	s_waitcnt vmcnt(25)
; __device__ __forceinline__ unsigned pk2(float lo, float hi) { const f32v2_t v = {lo, hi}; const bf16v2_t b = __builtin_convertvector(v, bf16v2_t); return __builtin_bit_cast(unsigned, b); }
; __device__ __forceinline__ float lo16(unsigned u) { return __uint_as_float(u << 16); }
; __device__ __forceinline__ float hi16(unsigned u) { return __uint_as_float(u & 0xffff0000u); }
; __device__ __forceinline__ float siluf_(float x) { return x * __builtin_amdgcn_rcpf(1.0f + __expf(-x)); }
; __device__ __forceinline__ void prep_dn_load(const bf16_t* proj, const float* cw, int idx, u32x4 (&raw)[4], int& t, int& ch) {
;     if (idx >= 0) { t = idx / 384; const int j = idx - t * 384; ch = j * 8; }
; #pragma unroll
;     for (int k = 0; k < 4; ++k) { const int tt = t - 3 + k; raw[k] = (u32x4){0u, 0u, 0u, 0u};
;         if (tt >= 0) raw[k] = *(const u32x4*)(proj + (size_t)tt * NP + C_DNQ + ch); }
; __device__ __forceinline__ void prep_dn_finish(const float* cw, bf16_t* dq, bf16_t* dk, bf16_t* dv, const u32x4 (&raw)[4], int t, int ch) {
;     float a[8];
; #pragma unroll
;     for (int e = 0; e < 8; ++e) a[e] = 0.f;
; #pragma unroll
;     for (int k = 0; k < 4; ++k) {
;         const f32x4 w0 = *(const f32x4*)(cw + k * 3072 + ch), w1 = *(const f32x4*)(cw + k * 3072 + ch + 4);
;         a[0] += w0[0] * lo16(raw[k].x); a[1] += w0[1] * hi16(raw[k].x); a[2] += w0[2] * lo16(raw[k].y); a[3] += w0[3] * hi16(raw[k].y);
;         a[4] += w1[0] * lo16(raw[k].z); a[5] += w1[1] * hi16(raw[k].z); a[6] += w1[2] * lo16(raw[k].w); a[7] += w1[3] * hi16(raw[k].w); }
;     float ss = 0.f;
; #pragma unroll
;     for (int e = 0; e < 8; ++e) { a[e] = siluf_(a[e]); ss += a[e] * a[e]; }
;     ss += __shfl_xor(ss, 1); ss += __shfl_xor(ss, 2); ss += __shfl_xor(ss, 4); ss += __shfl_xor(ss, 8);
;     float sc = 1.0f;
;     if (ch < 2048) { sc = rsqrtf(ss + EPS); if (ch < 1024) sc *= 0.08838834764831845f; }
;     u32x4 w; w.x = pk2(a[0] * sc, a[1] * sc); w.y = pk2(a[2] * sc, a[3] * sc); w.z = pk2(a[4] * sc, a[5] * sc); w.w = pk2(a[6] * sc, a[7] * sc);
;     bf16_t* dst = (ch < 1024) ? dq : (ch < 2048 ? dk : dv);
;     *(u32x4*)(dst + (size_t)t * 1024 + (ch & 1023)) = w;
	v_lshlrev_b32_e32 v146, 16, v92
	v_and_b32_e32 v147, 0xffff0000, v92
	v_lshlrev_b32_e32 v148, 16, v93
	v_and_b32_e32 v149, 0xffff0000, v93
	v_lshlrev_b32_e32 v150, 16, v94
	v_and_b32_e32 v151, 0xffff0000, v94
	v_lshlrev_b32_e32 v152, 16, v95
	v_and_b32_e32 v153, 0xffff0000, v95
	global_load_dwordx4 v[92:95], v1, s[100:101]
	s_sub_u32 s100, s100, 0x4ec00
	s_subb_u32 s101, s101, 0
	v_pk_mul_f32 v[162:163], v[96:97], v[154:155]
	v_pk_mul_f32 v[164:165], v[98:99], v[156:157]
	v_pk_mul_f32 v[166:167], v[100:101], v[158:159]
	v_pk_mul_f32 v[168:169], v[102:103], v[160:161]
	v_pk_fma_f32 v[162:163], v[104:105], v[128:129], v[162:163]
	v_pk_fma_f32 v[164:165], v[106:107], v[130:131], v[164:165]
	v_pk_fma_f32 v[166:167], v[108:109], v[132:133], v[166:167]
	v_pk_fma_f32 v[168:169], v[110:111], v[134:135], v[168:169]
	v_pk_fma_f32 v[162:163], v[112:113], v[136:137], v[162:163]
	v_pk_fma_f32 v[164:165], v[114:115], v[138:139], v[164:165]
	v_pk_fma_f32 v[166:167], v[116:117], v[140:141], v[166:167]
	v_pk_fma_f32 v[168:169], v[118:119], v[142:143], v[168:169]
	v_pk_fma_f32 v[162:163], v[120:121], v[146:147], v[162:163]
	v_pk_fma_f32 v[164:165], v[122:123], v[148:149], v[164:165]
	v_pk_fma_f32 v[166:167], v[124:125], v[150:151], v[166:167]
	v_pk_fma_f32 v[168:169], v[126:127], v[152:153], v[168:169]
	v_pk_mul_f32 v[40:41], v[162:163], s[12:13]
	v_pk_mul_f32 v[42:43], v[164:165], s[12:13]
	v_pk_mul_f32 v[44:45], v[166:167], s[12:13]
	v_pk_mul_f32 v[46:47], v[168:169], s[12:13]
	v_exp_f32_e32 v40, v40
	v_exp_f32_e32 v41, v41
	v_exp_f32_e32 v42, v42
	v_exp_f32_e32 v43, v43
	v_exp_f32_e32 v44, v44
	v_exp_f32_e32 v45, v45
	v_exp_f32_e32 v46, v46
	v_exp_f32_e32 v47, v47
	v_pk_add_f32 v[40:41], v[40:41], s[14:15]
	v_pk_add_f32 v[42:43], v[42:43], s[14:15]
	v_pk_add_f32 v[44:45], v[44:45], s[14:15]
	v_pk_add_f32 v[46:47], v[46:47], s[14:15]
	v_rcp_f32_e32 v40, v40
	v_rcp_f32_e32 v41, v41
	v_rcp_f32_e32 v42, v42
	v_rcp_f32_e32 v43, v43
	v_rcp_f32_e32 v44, v44
	v_rcp_f32_e32 v45, v45
	v_rcp_f32_e32 v46, v46
	v_rcp_f32_e32 v47, v47
	v_pk_mul_f32 v[162:163], v[162:163], v[40:41]
	v_pk_mul_f32 v[164:165], v[164:165], v[42:43]
	v_pk_mul_f32 v[166:167], v[166:167], v[44:45]
	v_pk_mul_f32 v[168:169], v[168:169], v[46:47]
	v_pk_mul_f32 v[40:41], v[162:163], v[162:163]
	v_pk_fma_f32 v[40:41], v[164:165], v[164:165], v[40:41]
	v_pk_fma_f32 v[40:41], v[166:167], v[166:167], v[40:41]
	v_pk_fma_f32 v[40:41], v[168:169], v[168:169], v[40:41]
	s_nop 0
	v_add_f32_e32 v50, v40, v41
	s_nop 1
	v_add_f32_dpp v50, v50, v50 quad_perm:[1,0,3,2] row_mask:0xf bank_mask:0xf
	s_nop 1
	v_add_f32_dpp v50, v50, v50 quad_perm:[2,3,0,1] row_mask:0xf bank_mask:0xf
	s_nop 1
	v_add_f32_dpp v50, v50, v50 row_half_mirror row_mask:0xf bank_mask:0xf
	s_nop 1
	v_add_f32_dpp v50, v50, v50 row_mirror row_mask:0xf bank_mask:0xf
	v_add_f32_e32 v50, 0x358637bd, v50
	v_rsq_f32_e32 v50, v50
	s_nop 0
	v_mul_f32_e32 v50, 0x3db504f3, v50
	v_pk_mul_f32 v[162:163], v[162:163], v[50:51] op_sel_hi:[1,0]
	v_pk_mul_f32 v[164:165], v[164:165], v[50:51] op_sel_hi:[1,0]
	v_pk_mul_f32 v[166:167], v[166:167], v[50:51] op_sel_hi:[1,0]
	v_pk_mul_f32 v[168:169], v[168:169], v[50:51] op_sel_hi:[1,0]
	v_cvt_pk_bf16_f32 v170, v162, v163
	v_cvt_pk_bf16_f32 v171, v164, v165
	v_cvt_pk_bf16_f32 v172, v166, v167
	v_cvt_pk_bf16_f32 v173, v168, v169
	global_store_dwordx4 v4, v[170:173], s[6:7]
	s_sub_u32 s6, s6, 0x3800
	s_subb_u32 s7, s7, 0
	s_add_u32 vcc_lo, s4, 0x2000
	s_addc_u32 vcc_hi, s5, 0
	global_load_dwordx4 v[96:99], v3, vcc
	global_load_dwordx4 v[100:103], v3, vcc offset:16
	s_add_u32 vcc_lo, s4, 0x5000
	s_addc_u32 vcc_hi, s5, 0
	global_load_dwordx4 v[104:107], v3, vcc
	global_load_dwordx4 v[108:111], v3, vcc offset:16
	s_add_u32 vcc_lo, s4, 0x8000
	s_addc_u32 vcc_hi, s5, 0
	global_load_dwordx4 v[112:115], v3, vcc
	global_load_dwordx4 v[116:119], v3, vcc offset:16
	s_add_u32 vcc_lo, s4, 0xb000
	s_addc_u32 vcc_hi, s5, 0
	global_load_dwordx4 v[120:123], v3, vcc
	global_load_dwordx4 v[124:127], v3, vcc offset:16
	s_waitcnt vmcnt(24)
	s_cmp_lt_i32 s10, 0
	s_cbranch_scc0 .Ldnc_nz1
	v_mov_b32_e32 v52, 0
	v_mov_b32_e32 v53, 0
	v_mov_b32_e32 v54, 0
	v_mov_b32_e32 v55, 0
	v_mov_b32_e32 v56, 0
	v_mov_b32_e32 v57, 0
	v_mov_b32_e32 v58, 0
	v_mov_b32_e32 v59, 0
	v_mov_b32_e32 v60, 0
	v_mov_b32_e32 v61, 0
	v_mov_b32_e32 v62, 0
	v_mov_b32_e32 v63, 0
; __device__ __forceinline__ unsigned pk2(float lo, float hi) { const f32v2_t v = {lo, hi}; const bf16v2_t b = __builtin_convertvector(v, bf16v2_t); return __builtin_bit_cast(unsigned, b); }
; __device__ __forceinline__ float lo16(unsigned u) { return __uint_as_float(u << 16); }
; __device__ __forceinline__ float hi16(unsigned u) { return __uint_as_float(u & 0xffff0000u); }
; __device__ __forceinline__ float siluf_(float x) { return x * __builtin_amdgcn_rcpf(1.0f + __expf(-x)); }
; __device__ __forceinline__ void prep_dn_load(const bf16_t* proj, const float* cw, int idx, u32x4 (&raw)[4], int& t, int& ch) {
;     if (idx >= 0) { t = idx / 384; const int j = idx - t * 384; ch = j * 8; }
; #pragma unroll
;     for (int k = 0; k < 4; ++k) { const int tt = t - 3 + k; raw[k] = (u32x4){0u, 0u, 0u, 0u};
;         if (tt >= 0) raw[k] = *(const u32x4*)(proj + (size_t)tt * NP + C_DNQ + ch); }
; }
; __device__ __forceinline__ void prep_dn_finish(const float* cw, bf16_t* dq, bf16_t* dk, bf16_t* dv, const u32x4 (&raw)[4], int t, int ch) {
;     float a[8];
; #pragma unroll
;     for (int e = 0; e < 8; ++e) a[e] = 0.f;
; #pragma unroll
;     for (int k = 0; k < 4; ++k) {
;         const f32x4 w0 = *(const f32x4*)(cw + k * 3072 + ch), w1 = *(const f32x4*)(cw + k * 3072 + ch + 4);
;         a[0] += w0[0] * lo16(raw[k].x); a[1] += w0[1] * hi16(raw[k].x); a[2] += w0[2] * lo16(raw[k].y); a[3] += w0[3] * hi16(raw[k].y);
;         a[4] += w1[0] * lo16(raw[k].z); a[5] += w1[1] * hi16(raw[k].z); a[6] += w1[2] * lo16(raw[k].w); a[7] += w1[3] * hi16(raw[k].w); }
;     float ss = 0.f;
; #pragma unroll
;     for (int e = 0; e < 8; ++e) { a[e] = siluf_(a[e]); ss += a[e] * a[e]; }
;     ss += __shfl_xor(ss, 1); ss += __shfl_xor(ss, 2); ss += __shfl_xor(ss, 4); ss += __shfl_xor(ss, 8);
;     float sc = 1.0f;
;     if (ch < 2048) { sc = rsqrtf(ss + EPS); if (ch < 1024) sc *= 0.08838834764831845f; }
;     u32x4 w; w.x = pk2(a[0] * sc, a[1] * sc); w.y = pk2(a[2] * sc, a[3] * sc); w.z = pk2(a[4] * sc, a[5] * sc); w.w = pk2(a[6] * sc, a[7] * sc);
;     bf16_t* dst = (ch < 1024) ? dq : (ch < 2048 ? dk : dv);
;     *(u32x4*)(dst + (size_t)t * 1024 + (ch & 1023)) = w;
.Ldnc_nz1:
	v_lshlrev_b32_e32 v128, 16, v52
	v_and_b32_e32 v129, 0xffff0000, v52
	v_lshlrev_b32_e32 v130, 16, v53
	v_and_b32_e32 v131, 0xffff0000, v53
	v_lshlrev_b32_e32 v132, 16, v54
	v_and_b32_e32 v133, 0xffff0000, v54
	v_lshlrev_b32_e32 v134, 16, v55
	v_and_b32_e32 v135, 0xffff0000, v55
	v_lshlrev_b32_e32 v136, 16, v56
	v_and_b32_e32 v137, 0xffff0000, v56
	v_lshlrev_b32_e32 v138, 16, v57
	v_and_b32_e32 v139, 0xffff0000, v57
	v_lshlrev_b32_e32 v140, 16, v58
	v_and_b32_e32 v141, 0xffff0000, v58
	v_lshlrev_b32_e32 v142, 16, v59
	v_and_b32_e32 v143, 0xffff0000, v59
	v_lshlrev_b32_e32 v146, 16, v60
	v_and_b32_e32 v147, 0xffff0000, v60
	v_lshlrev_b32_e32 v148, 16, v61
	v_and_b32_e32 v149, 0xffff0000, v61
	v_lshlrev_b32_e32 v150, 16, v62
	v_and_b32_e32 v151, 0xffff0000, v62
	v_lshlrev_b32_e32 v152, 16, v63
	v_and_b32_e32 v153, 0xffff0000, v63
	global_load_dwordx4 v[52:55], v2, s[100:101]
	s_add_u32 s100, s100, 0x7e00
	s_addc_u32 s101, s101, 0
	global_load_dwordx4 v[56:59], v2, s[100:101]
	s_add_u32 s100, s100, 0x7e00
	s_addc_u32 s101, s101, 0
	global_load_dwordx4 v[60:63], v2, s[100:101]
	s_add_u32 s100, s100, 0x7e00
	s_addc_u32 s101, s101, 0
	s_waitcnt vmcnt(26)
	v_lshlrev_b32_e32 v154, 16, v64
	v_and_b32_e32 v155, 0xffff0000, v64
	v_lshlrev_b32_e32 v156, 16, v65
	v_and_b32_e32 v157, 0xffff0000, v65
	v_lshlrev_b32_e32 v158, 16, v66
	v_and_b32_e32 v159, 0xffff0000, v66
	v_lshlrev_b32_e32 v160, 16, v67
	v_and_b32_e32 v161, 0xffff0000, v67
	global_load_dwordx4 v[64:67], v2, s[100:101]
	s_add_u32 s100, s100, 0x7e00
	s_addc_u32 s101, s101, 0
	v_pk_mul_f32 v[162:163], v[8:9], v[128:129]
	v_pk_mul_f32 v[164:165], v[10:11], v[130:131]
	v_pk_mul_f32 v[166:167], v[12:13], v[132:133]
	v_pk_mul_f32 v[168:169], v[14:15], v[134:135]
	v_pk_fma_f32 v[162:163], v[16:17], v[136:137], v[162:163]
	v_pk_fma_f32 v[164:165], v[18:19], v[138:139], v[164:165]
	v_pk_fma_f32 v[166:167], v[20:21], v[140:141], v[166:167]
	v_pk_fma_f32 v[168:169], v[22:23], v[142:143], v[168:169]
	v_pk_fma_f32 v[162:163], v[24:25], v[146:147], v[162:163]
	v_pk_fma_f32 v[164:165], v[26:27], v[148:149], v[164:165]
	v_pk_fma_f32 v[166:167], v[28:29], v[150:151], v[166:167]
	v_pk_fma_f32 v[168:169], v[30:31], v[152:153], v[168:169]
	v_pk_fma_f32 v[162:163], v[32:33], v[154:155], v[162:163]
	v_pk_fma_f32 v[164:165], v[34:35], v[156:157], v[164:165]
	v_pk_fma_f32 v[166:167], v[36:37], v[158:159], v[166:167]
	v_pk_fma_f32 v[168:169], v[38:39], v[160:161], v[168:169]
	v_pk_mul_f32 v[40:41], v[162:163], s[12:13]
	v_pk_mul_f32 v[42:43], v[164:165], s[12:13]
	v_pk_mul_f32 v[44:45], v[166:167], s[12:13]
	v_pk_mul_f32 v[46:47], v[168:169], s[12:13]
	v_exp_f32_e32 v40, v40
	v_exp_f32_e32 v41, v41
	v_exp_f32_e32 v42, v42
	v_exp_f32_e32 v43, v43
	v_exp_f32_e32 v44, v44
	v_exp_f32_e32 v45, v45
	v_exp_f32_e32 v46, v46
	v_exp_f32_e32 v47, v47
	v_pk_add_f32 v[40:41], v[40:41], s[14:15]
	v_pk_add_f32 v[42:43], v[42:43], s[14:15]
	v_pk_add_f32 v[44:45], v[44:45], s[14:15]
	v_pk_add_f32 v[46:47], v[46:47], s[14:15]
	v_rcp_f32_e32 v40, v40
	v_rcp_f32_e32 v41, v41
	v_rcp_f32_e32 v42, v42
	v_rcp_f32_e32 v43, v43
	v_rcp_f32_e32 v44, v44
	v_rcp_f32_e32 v45, v45
	v_rcp_f32_e32 v46, v46
	v_rcp_f32_e32 v47, v47
	v_pk_mul_f32 v[162:163], v[162:163], v[40:41]
	v_pk_mul_f32 v[164:165], v[164:165], v[42:43]
	v_pk_mul_f32 v[166:167], v[166:167], v[44:45]
	v_pk_mul_f32 v[168:169], v[168:169], v[46:47]
	v_pk_mul_f32 v[40:41], v[162:163], v[162:163]
	v_pk_fma_f32 v[40:41], v[164:165], v[164:165], v[40:41]
	v_pk_fma_f32 v[40:41], v[166:167], v[166:167], v[40:41]
	v_pk_fma_f32 v[40:41], v[168:169], v[168:169], v[40:41]
	s_nop 0
	v_add_f32_e32 v50, v40, v41
	s_nop 1
	v_add_f32_dpp v50, v50, v50 quad_perm:[1,0,3,2] row_mask:0xf bank_mask:0xf
	s_nop 1
	v_add_f32_dpp v50, v50, v50 quad_perm:[2,3,0,1] row_mask:0xf bank_mask:0xf
	s_nop 1
	v_add_f32_dpp v50, v50, v50 row_half_mirror row_mask:0xf bank_mask:0xf
	s_nop 1
	v_add_f32_dpp v50, v50, v50 row_mirror row_mask:0xf bank_mask:0xf
	v_add_f32_e32 v50, 0x358637bd, v50
	v_rsq_f32_e32 v50, v50
	s_nop 0
	v_pk_mul_f32 v[162:163], v[162:163], v[50:51] op_sel_hi:[1,0]
	v_pk_mul_f32 v[164:165], v[164:165], v[50:51] op_sel_hi:[1,0]
	v_pk_mul_f32 v[166:167], v[166:167], v[50:51] op_sel_hi:[1,0]
	v_pk_mul_f32 v[168:169], v[168:169], v[50:51] op_sel_hi:[1,0]
	v_cvt_pk_bf16_f32 v170, v162, v163
	v_cvt_pk_bf16_f32 v171, v164, v165
	v_cvt_pk_bf16_f32 v172, v166, v167
	v_cvt_pk_bf16_f32 v173, v168, v169
	global_store_dwordx4 v5, v[170:173], s[6:7]
	s_add_u32 s6, s6, 0x800
	s_addc_u32 s7, s7, 0
	s_waitcnt vmcnt(26)
; __device__ __forceinline__ unsigned pk2(float lo, float hi) { const f32v2_t v = {lo, hi}; const bf16v2_t b = __builtin_convertvector(v, bf16v2_t); return __builtin_bit_cast(unsigned, b); }
; __device__ __forceinline__ float lo16(unsigned u) { return __uint_as_float(u << 16); }
; __device__ __forceinline__ float hi16(unsigned u) { return __uint_as_float(u & 0xffff0000u); }
; __device__ __forceinline__ float siluf_(float x) { return x * __builtin_amdgcn_rcpf(1.0f + __expf(-x)); }
; __device__ __forceinline__ void prep_dn_finish(const float* cw, bf16_t* dq, bf16_t* dk, bf16_t* dv, const u32x4 (&raw)[4], int t, int ch) {
;     float a[8];
; #pragma unroll
;     for (int e = 0; e < 8; ++e) a[e] = 0.f;
; #pragma unroll
;     for (int k = 0; k < 4; ++k) {
;         const f32x4 w0 = *(const f32x4*)(cw + k * 3072 + ch), w1 = *(const f32x4*)(cw + k * 3072 + ch + 4);
;         a[0] += w0[0] * lo16(raw[k].x); a[1] += w0[1] * hi16(raw[k].x); a[2] += w0[2] * lo16(raw[k].y); a[3] += w0[3] * hi16(raw[k].y);
;         a[4] += w1[0] * lo16(raw[k].z); a[5] += w1[1] * hi16(raw[k].z); a[6] += w1[2] * lo16(raw[k].w); a[7] += w1[3] * hi16(raw[k].w); }
;     float ss = 0.f;
; #pragma unroll
;     for (int e = 0; e < 8; ++e) { a[e] = siluf_(a[e]); ss += a[e] * a[e]; }
;     ss += __shfl_xor(ss, 1); ss += __shfl_xor(ss, 2); ss += __shfl_xor(ss, 4); ss += __shfl_xor(ss, 8);
;     float sc = 1.0f;
;     if (ch < 2048) { sc = rsqrtf(ss + EPS); if (ch < 1024) sc *= 0.08838834764831845f; }
;     u32x4 w; w.x = pk2(a[0] * sc, a[1] * sc); w.y = pk2(a[2] * sc, a[3] * sc); w.z = pk2(a[4] * sc, a[5] * sc); w.w = pk2(a[6] * sc, a[7] * sc);
;     bf16_t* dst = (ch < 1024) ? dq : (ch < 2048 ? dk : dv);
;     *(u32x4*)(dst + (size_t)t * 1024 + (ch & 1023)) = w;
	v_lshlrev_b32_e32 v128, 16, v68
	v_and_b32_e32 v129, 0xffff0000, v68
	v_lshlrev_b32_e32 v130, 16, v69
	v_and_b32_e32 v131, 0xffff0000, v69
	v_lshlrev_b32_e32 v132, 16, v70
	v_and_b32_e32 v133, 0xffff0000, v70
	v_lshlrev_b32_e32 v134, 16, v71
	v_and_b32_e32 v135, 0xffff0000, v71
	global_load_dwordx4 v[68:71], v2, s[100:101]
	s_add_u32 s100, s100, 0x7e00
	s_addc_u32 s101, s101, 0
	v_pk_mul_f32 v[162:163], v[8:9], v[136:137]
	v_pk_mul_f32 v[164:165], v[10:11], v[138:139]
	v_pk_mul_f32 v[166:167], v[12:13], v[140:141]
	v_pk_mul_f32 v[168:169], v[14:15], v[142:143]
	v_pk_fma_f32 v[162:163], v[16:17], v[146:147], v[162:163]
	v_pk_fma_f32 v[164:165], v[18:19], v[148:149], v[164:165]
	v_pk_fma_f32 v[166:167], v[20:21], v[150:151], v[166:167]
	v_pk_fma_f32 v[168:169], v[22:23], v[152:153], v[168:169]
	v_pk_fma_f32 v[162:163], v[24:25], v[154:155], v[162:163]
	v_pk_fma_f32 v[164:165], v[26:27], v[156:157], v[164:165]
	v_pk_fma_f32 v[166:167], v[28:29], v[158:159], v[166:167]
	v_pk_fma_f32 v[168:169], v[30:31], v[160:161], v[168:169]
	v_pk_fma_f32 v[162:163], v[32:33], v[128:129], v[162:163]
	v_pk_fma_f32 v[164:165], v[34:35], v[130:131], v[164:165]
	v_pk_fma_f32 v[166:167], v[36:37], v[132:133], v[166:167]
	v_pk_fma_f32 v[168:169], v[38:39], v[134:135], v[168:169]
	v_pk_mul_f32 v[40:41], v[162:163], s[12:13]
	v_pk_mul_f32 v[42:43], v[164:165], s[12:13]
	v_pk_mul_f32 v[44:45], v[166:167], s[12:13]
	v_pk_mul_f32 v[46:47], v[168:169], s[12:13]
	v_exp_f32_e32 v40, v40
	v_exp_f32_e32 v41, v41
	v_exp_f32_e32 v42, v42
	v_exp_f32_e32 v43, v43
	v_exp_f32_e32 v44, v44
	v_exp_f32_e32 v45, v45
	v_exp_f32_e32 v46, v46
	v_exp_f32_e32 v47, v47
	v_pk_add_f32 v[40:41], v[40:41], s[14:15]
	v_pk_add_f32 v[42:43], v[42:43], s[14:15]
	v_pk_add_f32 v[44:45], v[44:45], s[14:15]
	v_pk_add_f32 v[46:47], v[46:47], s[14:15]
	v_rcp_f32_e32 v40, v40
	v_rcp_f32_e32 v41, v41
	v_rcp_f32_e32 v42, v42
	v_rcp_f32_e32 v43, v43
	v_rcp_f32_e32 v44, v44
	v_rcp_f32_e32 v45, v45
	v_rcp_f32_e32 v46, v46
	v_rcp_f32_e32 v47, v47
	v_pk_mul_f32 v[162:163], v[162:163], v[40:41]
	v_pk_mul_f32 v[164:165], v[164:165], v[42:43]
	v_pk_mul_f32 v[166:167], v[166:167], v[44:45]
	v_pk_mul_f32 v[168:169], v[168:169], v[46:47]
	v_pk_mul_f32 v[40:41], v[162:163], v[162:163]
	v_pk_fma_f32 v[40:41], v[164:165], v[164:165], v[40:41]
	v_pk_fma_f32 v[40:41], v[166:167], v[166:167], v[40:41]
	v_pk_fma_f32 v[40:41], v[168:169], v[168:169], v[40:41]
	s_nop 0
	v_add_f32_e32 v50, v40, v41
	s_nop 1
	v_add_f32_dpp v50, v50, v50 quad_perm:[1,0,3,2] row_mask:0xf bank_mask:0xf
	s_nop 1
	v_add_f32_dpp v50, v50, v50 quad_perm:[2,3,0,1] row_mask:0xf bank_mask:0xf
	s_nop 1
	v_add_f32_dpp v50, v50, v50 row_half_mirror row_mask:0xf bank_mask:0xf
	s_nop 1
	v_add_f32_dpp v50, v50, v50 row_mirror row_mask:0xf bank_mask:0xf
	v_add_f32_e32 v50, 0x358637bd, v50
	v_rsq_f32_e32 v50, v50
	s_nop 0
	v_pk_mul_f32 v[162:163], v[162:163], v[50:51] op_sel_hi:[1,0]
	v_pk_mul_f32 v[164:165], v[164:165], v[50:51] op_sel_hi:[1,0]
	v_pk_mul_f32 v[166:167], v[166:167], v[50:51] op_sel_hi:[1,0]
	v_pk_mul_f32 v[168:169], v[168:169], v[50:51] op_sel_hi:[1,0]
	v_cvt_pk_bf16_f32 v170, v162, v163
	v_cvt_pk_bf16_f32 v171, v164, v165
	v_cvt_pk_bf16_f32 v172, v166, v167
	v_cvt_pk_bf16_f32 v173, v168, v169
	global_store_dwordx4 v5, v[170:173], s[6:7]
	s_add_u32 s6, s6, 0x800
	s_addc_u32 s7, s7, 0
	s_waitcnt vmcnt(26)
	v_lshlrev_b32_e32 v136, 16, v72
	v_and_b32_e32 v137, 0xffff0000, v72
	v_lshlrev_b32_e32 v138, 16, v73
	v_and_b32_e32 v139, 0xffff0000, v73
	v_lshlrev_b32_e32 v140, 16, v74
	v_and_b32_e32 v141, 0xffff0000, v74
	v_lshlrev_b32_e32 v142, 16, v75
	v_and_b32_e32 v143, 0xffff0000, v75
	global_load_dwordx4 v[72:75], v2, s[100:101]
	s_add_u32 s100, s100, 0x7e00
	s_addc_u32 s101, s101, 0
	v_pk_mul_f32 v[162:163], v[8:9], v[146:147]
	v_pk_mul_f32 v[164:165], v[10:11], v[148:149]
	v_pk_mul_f32 v[166:167], v[12:13], v[150:151]
	v_pk_mul_f32 v[168:169], v[14:15], v[152:153]
	v_pk_fma_f32 v[162:163], v[16:17], v[154:155], v[162:163]
	v_pk_fma_f32 v[164:165], v[18:19], v[156:157], v[164:165]
	v_pk_fma_f32 v[166:167], v[20:21], v[158:159], v[166:167]
	v_pk_fma_f32 v[168:169], v[22:23], v[160:161], v[168:169]
	v_pk_fma_f32 v[162:163], v[24:25], v[128:129], v[162:163]
	v_pk_fma_f32 v[164:165], v[26:27], v[130:131], v[164:165]
	v_pk_fma_f32 v[166:167], v[28:29], v[132:133], v[166:167]
	v_pk_fma_f32 v[168:169], v[30:31], v[134:135], v[168:169]
	v_pk_fma_f32 v[162:163], v[32:33], v[136:137], v[162:163]
	v_pk_fma_f32 v[164:165], v[34:35], v[138:139], v[164:165]
	v_pk_fma_f32 v[166:167], v[36:37], v[140:141], v[166:167]
	v_pk_fma_f32 v[168:169], v[38:39], v[142:143], v[168:169]
	v_pk_mul_f32 v[40:41], v[162:163], s[12:13]
	v_pk_mul_f32 v[42:43], v[164:165], s[12:13]
	v_pk_mul_f32 v[44:45], v[166:167], s[12:13]
	v_pk_mul_f32 v[46:47], v[168:169], s[12:13]
	v_exp_f32_e32 v40, v40
	v_exp_f32_e32 v41, v41
	v_exp_f32_e32 v42, v42
	v_exp_f32_e32 v43, v43
	v_exp_f32_e32 v44, v44
	v_exp_f32_e32 v45, v45
	v_exp_f32_e32 v46, v46
	v_exp_f32_e32 v47, v47
	v_pk_add_f32 v[40:41], v[40:41], s[14:15]
	v_pk_add_f32 v[42:43], v[42:43], s[14:15]
	v_pk_add_f32 v[44:45], v[44:45], s[14:15]
	v_pk_add_f32 v[46:47], v[46:47], s[14:15]
	v_rcp_f32_e32 v40, v40
	v_rcp_f32_e32 v41, v41
	v_rcp_f32_e32 v42, v42
	v_rcp_f32_e32 v43, v43
	v_rcp_f32_e32 v44, v44
	v_rcp_f32_e32 v45, v45
	v_rcp_f32_e32 v46, v46
	v_rcp_f32_e32 v47, v47
	v_pk_mul_f32 v[162:163], v[162:163], v[40:41]
	v_pk_mul_f32 v[164:165], v[164:165], v[42:43]
	v_pk_mul_f32 v[166:167], v[166:167], v[44:45]
	v_pk_mul_f32 v[168:169], v[168:169], v[46:47]
	v_pk_mul_f32 v[40:41], v[162:163], v[162:163]
	v_pk_fma_f32 v[40:41], v[164:165], v[164:165], v[40:41]
	v_pk_fma_f32 v[40:41], v[166:167], v[166:167], v[40:41]
	v_pk_fma_f32 v[40:41], v[168:169], v[168:169], v[40:41]
	s_nop 0
	v_add_f32_e32 v50, v40, v41
	s_nop 1
	v_add_f32_dpp v50, v50, v50 quad_perm:[1,0,3,2] row_mask:0xf bank_mask:0xf
	s_nop 1
	v_add_f32_dpp v50, v50, v50 quad_perm:[2,3,0,1] row_mask:0xf bank_mask:0xf
	s_nop 1
	v_add_f32_dpp v50, v50, v50 row_half_mirror row_mask:0xf bank_mask:0xf
	s_nop 1
	v_add_f32_dpp v50, v50, v50 row_mirror row_mask:0xf bank_mask:0xf
	v_add_f32_e32 v50, 0x358637bd, v50
	v_rsq_f32_e32 v50, v50
	s_nop 0
	v_pk_mul_f32 v[162:163], v[162:163], v[50:51] op_sel_hi:[1,0]
	v_pk_mul_f32 v[164:165], v[164:165], v[50:51] op_sel_hi:[1,0]
	v_pk_mul_f32 v[166:167], v[166:167], v[50:51] op_sel_hi:[1,0]
	v_pk_mul_f32 v[168:169], v[168:169], v[50:51] op_sel_hi:[1,0]
	v_cvt_pk_bf16_f32 v170, v162, v163
	v_cvt_pk_bf16_f32 v171, v164, v165
	v_cvt_pk_bf16_f32 v172, v166, v167
	v_cvt_pk_bf16_f32 v173, v168, v169
	global_store_dwordx4 v5, v[170:173], s[6:7]
	s_add_u32 s6, s6, 0x800
	s_addc_u32 s7, s7, 0
	s_waitcnt vmcnt(26)
; __device__ __forceinline__ unsigned pk2(float lo, float hi) { const f32v2_t v = {lo, hi}; const bf16v2_t b = __builtin_convertvector(v, bf16v2_t); return __builtin_bit_cast(unsigned, b); }
; __device__ __forceinline__ float lo16(unsigned u) { return __uint_as_float(u << 16); }
; __device__ __forceinline__ float hi16(unsigned u) { return __uint_as_float(u & 0xffff0000u); }
; __device__ __forceinline__ float siluf_(float x) { return x * __builtin_amdgcn_rcpf(1.0f + __expf(-x)); }
; __device__ __forceinline__ void prep_dn_load(const bf16_t* proj, const float* cw, int idx, u32x4 (&raw)[4], int& t, int& ch) {
;     if (idx >= 0) { t = idx / 384; const int j = idx - t * 384; ch = j * 8; }
; #pragma unroll
;     for (int k = 0; k < 4; ++k) { const int tt = t - 3 + k; raw[k] = (u32x4){0u, 0u, 0u, 0u};
;         if (tt >= 0) raw[k] = *(const u32x4*)(proj + (size_t)tt * NP + C_DNQ + ch); }
; }
; __device__ __forceinline__ void prep_dn_finish(const float* cw, bf16_t* dq, bf16_t* dk, bf16_t* dv, const u32x4 (&raw)[4], int t, int ch) {
;     float a[8];
; #pragma unroll
;     for (int e = 0; e < 8; ++e) a[e] = 0.f;
; #pragma unroll
;     for (int k = 0; k < 4; ++k) {
;         const f32x4 w0 = *(const f32x4*)(cw + k * 3072 + ch), w1 = *(const f32x4*)(cw + k * 3072 + ch + 4);
;         a[0] += w0[0] * lo16(raw[k].x); a[1] += w0[1] * hi16(raw[k].x); a[2] += w0[2] * lo16(raw[k].y); a[3] += w0[3] * hi16(raw[k].y);
;         a[4] += w1[0] * lo16(raw[k].z); a[5] += w1[1] * hi16(raw[k].z); a[6] += w1[2] * lo16(raw[k].w); a[7] += w1[3] * hi16(raw[k].w); }
;     float ss = 0.f;
; #pragma unroll
;     for (int e = 0; e < 8; ++e) { a[e] = siluf_(a[e]); ss += a[e] * a[e]; }
;     ss += __shfl_xor(ss, 1); ss += __shfl_xor(ss, 2); ss += __shfl_xor(ss, 4); ss += __shfl_xor(ss, 8);
;     float sc = 1.0f;
;     if (ch < 2048) { sc = rsqrtf(ss + EPS); if (ch < 1024) sc *= 0.08838834764831845f; }
;     u32x4 w; w.x = pk2(a[0] * sc, a[1] * sc); w.y = pk2(a[2] * sc, a[3] * sc); w.z = pk2(a[4] * sc, a[5] * sc); w.w = pk2(a[6] * sc, a[7] * sc);
;     bf16_t* dst = (ch < 1024) ? dq : (ch < 2048 ? dk : dv);
;     *(u32x4*)(dst + (size_t)t * 1024 + (ch & 1023)) = w;
; }
	v_lshlrev_b32_e32 v146, 16, v76
	v_and_b32_e32 v147, 0xffff0000, v76
	v_lshlrev_b32_e32 v148, 16, v77
	v_and_b32_e32 v149, 0xffff0000, v77
	v_lshlrev_b32_e32 v150, 16, v78
	v_and_b32_e32 v151, 0xffff0000, v78
	v_lshlrev_b32_e32 v152, 16, v79
	v_and_b32_e32 v153, 0xffff0000, v79
	global_load_dwordx4 v[76:79], v2, s[100:101]
	s_add_u32 s100, s100, 0x7e00
	s_addc_u32 s101, s101, 0
	v_pk_mul_f32 v[162:163], v[8:9], v[154:155]
	v_pk_mul_f32 v[164:165], v[10:11], v[156:157]
	v_pk_mul_f32 v[166:167], v[12:13], v[158:159]
	v_pk_mul_f32 v[168:169], v[14:15], v[160:161]
	v_pk_fma_f32 v[162:163], v[16:17], v[128:129], v[162:163]
	v_pk_fma_f32 v[164:165], v[18:19], v[130:131], v[164:165]
	v_pk_fma_f32 v[166:167], v[20:21], v[132:133], v[166:167]
	v_pk_fma_f32 v[168:169], v[22:23], v[134:135], v[168:169]
	v_pk_fma_f32 v[162:163], v[24:25], v[136:137], v[162:163]
	v_pk_fma_f32 v[164:165], v[26:27], v[138:139], v[164:165]
	v_pk_fma_f32 v[166:167], v[28:29], v[140:141], v[166:167]
	v_pk_fma_f32 v[168:169], v[30:31], v[142:143], v[168:169]
	v_pk_fma_f32 v[162:163], v[32:33], v[146:147], v[162:163]
	v_pk_fma_f32 v[164:165], v[34:35], v[148:149], v[164:165]
	v_pk_fma_f32 v[166:167], v[36:37], v[150:151], v[166:167]
	v_pk_fma_f32 v[168:169], v[38:39], v[152:153], v[168:169]
	v_pk_mul_f32 v[40:41], v[162:163], s[12:13]
	v_pk_mul_f32 v[42:43], v[164:165], s[12:13]
	v_pk_mul_f32 v[44:45], v[166:167], s[12:13]
	v_pk_mul_f32 v[46:47], v[168:169], s[12:13]
	v_exp_f32_e32 v40, v40
	v_exp_f32_e32 v41, v41
	v_exp_f32_e32 v42, v42
	v_exp_f32_e32 v43, v43
	v_exp_f32_e32 v44, v44
	v_exp_f32_e32 v45, v45
	v_exp_f32_e32 v46, v46
	v_exp_f32_e32 v47, v47
	v_pk_add_f32 v[40:41], v[40:41], s[14:15]
	v_pk_add_f32 v[42:43], v[42:43], s[14:15]
	v_pk_add_f32 v[44:45], v[44:45], s[14:15]
	v_pk_add_f32 v[46:47], v[46:47], s[14:15]
	v_rcp_f32_e32 v40, v40
	v_rcp_f32_e32 v41, v41
	v_rcp_f32_e32 v42, v42
	v_rcp_f32_e32 v43, v43
	v_rcp_f32_e32 v44, v44
	v_rcp_f32_e32 v45, v45
	v_rcp_f32_e32 v46, v46
	v_rcp_f32_e32 v47, v47
	v_pk_mul_f32 v[162:163], v[162:163], v[40:41]
	v_pk_mul_f32 v[164:165], v[164:165], v[42:43]
	v_pk_mul_f32 v[166:167], v[166:167], v[44:45]
	v_pk_mul_f32 v[168:169], v[168:169], v[46:47]
	v_pk_mul_f32 v[40:41], v[162:163], v[162:163]
	v_pk_fma_f32 v[40:41], v[164:165], v[164:165], v[40:41]
	v_pk_fma_f32 v[40:41], v[166:167], v[166:167], v[40:41]
	v_pk_fma_f32 v[40:41], v[168:169], v[168:169], v[40:41]
	s_nop 0
	v_add_f32_e32 v50, v40, v41
	s_nop 1
	v_add_f32_dpp v50, v50, v50 quad_perm:[1,0,3,2] row_mask:0xf bank_mask:0xf
	s_nop 1
	v_add_f32_dpp v50, v50, v50 quad_perm:[2,3,0,1] row_mask:0xf bank_mask:0xf
	s_nop 1
	v_add_f32_dpp v50, v50, v50 row_half_mirror row_mask:0xf bank_mask:0xf
	s_nop 1
	v_add_f32_dpp v50, v50, v50 row_mirror row_mask:0xf bank_mask:0xf
	v_add_f32_e32 v50, 0x358637bd, v50
	v_rsq_f32_e32 v50, v50
	s_nop 0
	v_pk_mul_f32 v[162:163], v[162:163], v[50:51] op_sel_hi:[1,0]
	v_pk_mul_f32 v[164:165], v[164:165], v[50:51] op_sel_hi:[1,0]
	v_pk_mul_f32 v[166:167], v[166:167], v[50:51] op_sel_hi:[1,0]
	v_pk_mul_f32 v[168:169], v[168:169], v[50:51] op_sel_hi:[1,0]
	v_cvt_pk_bf16_f32 v170, v162, v163
	v_cvt_pk_bf16_f32 v171, v164, v165
	v_cvt_pk_bf16_f32 v172, v166, v167
	v_cvt_pk_bf16_f32 v173, v168, v169
	global_store_dwordx4 v5, v[170:173], s[6:7]
	s_add_u32 s6, s6, 0x800
	s_addc_u32 s7, s7, 0
	s_waitcnt vmcnt(26)
	v_lshlrev_b32_e32 v154, 16, v80
	v_and_b32_e32 v155, 0xffff0000, v80
	v_lshlrev_b32_e32 v156, 16, v81
	v_and_b32_e32 v157, 0xffff0000, v81
	v_lshlrev_b32_e32 v158, 16, v82
	v_and_b32_e32 v159, 0xffff0000, v82
	v_lshlrev_b32_e32 v160, 16, v83
	v_and_b32_e32 v161, 0xffff0000, v83
	global_load_dwordx4 v[80:83], v2, s[100:101]
	s_add_u32 s100, s100, 0x7e00
	s_addc_u32 s101, s101, 0
	v_pk_mul_f32 v[162:163], v[8:9], v[128:129]
	v_pk_mul_f32 v[164:165], v[10:11], v[130:131]
	v_pk_mul_f32 v[166:167], v[12:13], v[132:133]
	v_pk_mul_f32 v[168:169], v[14:15], v[134:135]
	v_pk_fma_f32 v[162:163], v[16:17], v[136:137], v[162:163]
	v_pk_fma_f32 v[164:165], v[18:19], v[138:139], v[164:165]
	v_pk_fma_f32 v[166:167], v[20:21], v[140:141], v[166:167]
	v_pk_fma_f32 v[168:169], v[22:23], v[142:143], v[168:169]
	v_pk_fma_f32 v[162:163], v[24:25], v[146:147], v[162:163]
	v_pk_fma_f32 v[164:165], v[26:27], v[148:149], v[164:165]
	v_pk_fma_f32 v[166:167], v[28:29], v[150:151], v[166:167]
	v_pk_fma_f32 v[168:169], v[30:31], v[152:153], v[168:169]
	v_pk_fma_f32 v[162:163], v[32:33], v[154:155], v[162:163]
	v_pk_fma_f32 v[164:165], v[34:35], v[156:157], v[164:165]
	v_pk_fma_f32 v[166:167], v[36:37], v[158:159], v[166:167]
	v_pk_fma_f32 v[168:169], v[38:39], v[160:161], v[168:169]
	v_pk_mul_f32 v[40:41], v[162:163], s[12:13]
	v_pk_mul_f32 v[42:43], v[164:165], s[12:13]
	v_pk_mul_f32 v[44:45], v[166:167], s[12:13]
	v_pk_mul_f32 v[46:47], v[168:169], s[12:13]
	v_exp_f32_e32 v40, v40
	v_exp_f32_e32 v41, v41
	v_exp_f32_e32 v42, v42
	v_exp_f32_e32 v43, v43
	v_exp_f32_e32 v44, v44
	v_exp_f32_e32 v45, v45
	v_exp_f32_e32 v46, v46
	v_exp_f32_e32 v47, v47
	v_pk_add_f32 v[40:41], v[40:41], s[14:15]
	v_pk_add_f32 v[42:43], v[42:43], s[14:15]
	v_pk_add_f32 v[44:45], v[44:45], s[14:15]
	v_pk_add_f32 v[46:47], v[46:47], s[14:15]
	v_rcp_f32_e32 v40, v40
	v_rcp_f32_e32 v41, v41
	v_rcp_f32_e32 v42, v42
	v_rcp_f32_e32 v43, v43
	v_rcp_f32_e32 v44, v44
	v_rcp_f32_e32 v45, v45
	v_rcp_f32_e32 v46, v46
	v_rcp_f32_e32 v47, v47
	v_pk_mul_f32 v[162:163], v[162:163], v[40:41]
	v_pk_mul_f32 v[164:165], v[164:165], v[42:43]
	v_pk_mul_f32 v[166:167], v[166:167], v[44:45]
	v_pk_mul_f32 v[168:169], v[168:169], v[46:47]
	v_pk_mul_f32 v[40:41], v[162:163], v[162:163]
	v_pk_fma_f32 v[40:41], v[164:165], v[164:165], v[40:41]
	v_pk_fma_f32 v[40:41], v[166:167], v[166:167], v[40:41]
	v_pk_fma_f32 v[40:41], v[168:169], v[168:169], v[40:41]
	s_nop 0
	v_add_f32_e32 v50, v40, v41
	s_nop 1
	v_add_f32_dpp v50, v50, v50 quad_perm:[1,0,3,2] row_mask:0xf bank_mask:0xf
	s_nop 1
	v_add_f32_dpp v50, v50, v50 quad_perm:[2,3,0,1] row_mask:0xf bank_mask:0xf
	s_nop 1
	v_add_f32_dpp v50, v50, v50 row_half_mirror row_mask:0xf bank_mask:0xf
	s_nop 1
	v_add_f32_dpp v50, v50, v50 row_mirror row_mask:0xf bank_mask:0xf
	v_add_f32_e32 v50, 0x358637bd, v50
	v_rsq_f32_e32 v50, v50
	s_nop 0
	v_pk_mul_f32 v[162:163], v[162:163], v[50:51] op_sel_hi:[1,0]
	v_pk_mul_f32 v[164:165], v[164:165], v[50:51] op_sel_hi:[1,0]
	v_pk_mul_f32 v[166:167], v[166:167], v[50:51] op_sel_hi:[1,0]
	v_pk_mul_f32 v[168:169], v[168:169], v[50:51] op_sel_hi:[1,0]
	v_cvt_pk_bf16_f32 v170, v162, v163
	v_cvt_pk_bf16_f32 v171, v164, v165
	v_cvt_pk_bf16_f32 v172, v166, v167
	v_cvt_pk_bf16_f32 v173, v168, v169
	global_store_dwordx4 v5, v[170:173], s[6:7]
	s_add_u32 s6, s6, 0x800
	s_addc_u32 s7, s7, 0
	s_waitcnt vmcnt(26)
; __device__ __forceinline__ unsigned pk2(float lo, float hi) { const f32v2_t v = {lo, hi}; const bf16v2_t b = __builtin_convertvector(v, bf16v2_t); return __builtin_bit_cast(unsigned, b); }
; __device__ __forceinline__ float lo16(unsigned u) { return __uint_as_float(u << 16); }
; __device__ __forceinline__ float hi16(unsigned u) { return __uint_as_float(u & 0xffff0000u); }
; __device__ __forceinline__ float siluf_(float x) { return x * __builtin_amdgcn_rcpf(1.0f + __expf(-x)); }
; __device__ __forceinline__ void prep_dn_load(const bf16_t* proj, const float* cw, int idx, u32x4 (&raw)[4], int& t, int& ch) {
;     if (idx >= 0) { t = idx / 384; const int j = idx - t * 384; ch = j * 8; }
; #pragma unroll
;     for (int k = 0; k < 4; ++k) { const int tt = t - 3 + k; raw[k] = (u32x4){0u, 0u, 0u, 0u};
;         if (tt >= 0) raw[k] = *(const u32x4*)(proj + (size_t)tt * NP + C_DNQ + ch); }
; }
; __device__ __forceinline__ void prep_dn_finish(const float* cw, bf16_t* dq, bf16_t* dk, bf16_t* dv, const u32x4 (&raw)[4], int t, int ch) {
;     float a[8];
; #pragma unroll
;     for (int e = 0; e < 8; ++e) a[e] = 0.f;
; #pragma unroll
;     for (int k = 0; k < 4; ++k) {
;         const f32x4 w0 = *(const f32x4*)(cw + k * 3072 + ch), w1 = *(const f32x4*)(cw + k * 3072 + ch + 4);
;         a[0] += w0[0] * lo16(raw[k].x); a[1] += w0[1] * hi16(raw[k].x); a[2] += w0[2] * lo16(raw[k].y); a[3] += w0[3] * hi16(raw[k].y);
;         a[4] += w1[0] * lo16(raw[k].z); a[5] += w1[1] * hi16(raw[k].z); a[6] += w1[2] * lo16(raw[k].w); a[7] += w1[3] * hi16(raw[k].w); }
;     float ss = 0.f;
; #pragma unroll
;     for (int e = 0; e < 8; ++e) { a[e] = siluf_(a[e]); ss += a[e] * a[e]; }
;     ss += __shfl_xor(ss, 1); ss += __shfl_xor(ss, 2); ss += __shfl_xor(ss, 4); ss += __shfl_xor(ss, 8);
;     float sc = 1.0f;
;     if (ch < 2048) { sc = rsqrtf(ss + EPS); if (ch < 1024) sc *= 0.08838834764831845f; }
;     u32x4 w; w.x = pk2(a[0] * sc, a[1] * sc); w.y = pk2(a[2] * sc, a[3] * sc); w.z = pk2(a[4] * sc, a[5] * sc); w.w = pk2(a[6] * sc, a[7] * sc);
;     bf16_t* dst = (ch < 1024) ? dq : (ch < 2048 ? dk : dv);
;     *(u32x4*)(dst + (size_t)t * 1024 + (ch & 1023)) = w;
; }
	v_lshlrev_b32_e32 v128, 16, v84
	v_and_b32_e32 v129, 0xffff0000, v84
	v_lshlrev_b32_e32 v130, 16, v85
	v_and_b32_e32 v131, 0xffff0000, v85
	v_lshlrev_b32_e32 v132, 16, v86
	v_and_b32_e32 v133, 0xffff0000, v86
	v_lshlrev_b32_e32 v134, 16, v87
	v_and_b32_e32 v135, 0xffff0000, v87
	global_load_dwordx4 v[84:87], v2, s[100:101]
	s_add_u32 s100, s100, 0x7e00
	s_addc_u32 s101, s101, 0
	v_pk_mul_f32 v[162:163], v[8:9], v[136:137]
	v_pk_mul_f32 v[164:165], v[10:11], v[138:139]
	v_pk_mul_f32 v[166:167], v[12:13], v[140:141]
	v_pk_mul_f32 v[168:169], v[14:15], v[142:143]
	v_pk_fma_f32 v[162:163], v[16:17], v[146:147], v[162:163]
	v_pk_fma_f32 v[164:165], v[18:19], v[148:149], v[164:165]
	v_pk_fma_f32 v[166:167], v[20:21], v[150:151], v[166:167]
	v_pk_fma_f32 v[168:169], v[22:23], v[152:153], v[168:169]
	v_pk_fma_f32 v[162:163], v[24:25], v[154:155], v[162:163]
	v_pk_fma_f32 v[164:165], v[26:27], v[156:157], v[164:165]
	v_pk_fma_f32 v[166:167], v[28:29], v[158:159], v[166:167]
	v_pk_fma_f32 v[168:169], v[30:31], v[160:161], v[168:169]
	v_pk_fma_f32 v[162:163], v[32:33], v[128:129], v[162:163]
	v_pk_fma_f32 v[164:165], v[34:35], v[130:131], v[164:165]
	v_pk_fma_f32 v[166:167], v[36:37], v[132:133], v[166:167]
	v_pk_fma_f32 v[168:169], v[38:39], v[134:135], v[168:169]
	v_pk_mul_f32 v[40:41], v[162:163], s[12:13]
	v_pk_mul_f32 v[42:43], v[164:165], s[12:13]
	v_pk_mul_f32 v[44:45], v[166:167], s[12:13]
	v_pk_mul_f32 v[46:47], v[168:169], s[12:13]
	v_exp_f32_e32 v40, v40
	v_exp_f32_e32 v41, v41
	v_exp_f32_e32 v42, v42
	v_exp_f32_e32 v43, v43
	v_exp_f32_e32 v44, v44
	v_exp_f32_e32 v45, v45
	v_exp_f32_e32 v46, v46
	v_exp_f32_e32 v47, v47
	v_pk_add_f32 v[40:41], v[40:41], s[14:15]
	v_pk_add_f32 v[42:43], v[42:43], s[14:15]
	v_pk_add_f32 v[44:45], v[44:45], s[14:15]
	v_pk_add_f32 v[46:47], v[46:47], s[14:15]
	v_rcp_f32_e32 v40, v40
	v_rcp_f32_e32 v41, v41
	v_rcp_f32_e32 v42, v42
	v_rcp_f32_e32 v43, v43
	v_rcp_f32_e32 v44, v44
	v_rcp_f32_e32 v45, v45
	v_rcp_f32_e32 v46, v46
	v_rcp_f32_e32 v47, v47
	v_pk_mul_f32 v[162:163], v[162:163], v[40:41]
	v_pk_mul_f32 v[164:165], v[164:165], v[42:43]
	v_pk_mul_f32 v[166:167], v[166:167], v[44:45]
	v_pk_mul_f32 v[168:169], v[168:169], v[46:47]
	v_pk_mul_f32 v[40:41], v[162:163], v[162:163]
	v_pk_fma_f32 v[40:41], v[164:165], v[164:165], v[40:41]
	v_pk_fma_f32 v[40:41], v[166:167], v[166:167], v[40:41]
	v_pk_fma_f32 v[40:41], v[168:169], v[168:169], v[40:41]
	s_nop 0
	v_add_f32_e32 v50, v40, v41
	s_nop 1
	v_add_f32_dpp v50, v50, v50 quad_perm:[1,0,3,2] row_mask:0xf bank_mask:0xf
	s_nop 1
	v_add_f32_dpp v50, v50, v50 quad_perm:[2,3,0,1] row_mask:0xf bank_mask:0xf
	s_nop 1
	v_add_f32_dpp v50, v50, v50 row_half_mirror row_mask:0xf bank_mask:0xf
	s_nop 1
	v_add_f32_dpp v50, v50, v50 row_mirror row_mask:0xf bank_mask:0xf
	v_add_f32_e32 v50, 0x358637bd, v50
	v_rsq_f32_e32 v50, v50
	s_nop 0
	v_pk_mul_f32 v[162:163], v[162:163], v[50:51] op_sel_hi:[1,0]
	v_pk_mul_f32 v[164:165], v[164:165], v[50:51] op_sel_hi:[1,0]
	v_pk_mul_f32 v[166:167], v[166:167], v[50:51] op_sel_hi:[1,0]
	v_pk_mul_f32 v[168:169], v[168:169], v[50:51] op_sel_hi:[1,0]
	v_cvt_pk_bf16_f32 v170, v162, v163
	v_cvt_pk_bf16_f32 v171, v164, v165
	v_cvt_pk_bf16_f32 v172, v166, v167
	v_cvt_pk_bf16_f32 v173, v168, v169
	global_store_dwordx4 v5, v[170:173], s[6:7]
	s_add_u32 s6, s6, 0x800
	s_addc_u32 s7, s7, 0
	s_waitcnt vmcnt(26)
	v_lshlrev_b32_e32 v136, 16, v88
	v_and_b32_e32 v137, 0xffff0000, v88
	v_lshlrev_b32_e32 v138, 16, v89
	v_and_b32_e32 v139, 0xffff0000, v89
	v_lshlrev_b32_e32 v140, 16, v90
	v_and_b32_e32 v141, 0xffff0000, v90
	v_lshlrev_b32_e32 v142, 16, v91
	v_and_b32_e32 v143, 0xffff0000, v91
	global_load_dwordx4 v[88:91], v2, s[100:101]
	s_add_u32 s100, s100, 0x7e00
	s_addc_u32 s101, s101, 0
	v_pk_mul_f32 v[162:163], v[8:9], v[146:147]
	v_pk_mul_f32 v[164:165], v[10:11], v[148:149]
	v_pk_mul_f32 v[166:167], v[12:13], v[150:151]
	v_pk_mul_f32 v[168:169], v[14:15], v[152:153]
	v_pk_fma_f32 v[162:163], v[16:17], v[154:155], v[162:163]
	v_pk_fma_f32 v[164:165], v[18:19], v[156:157], v[164:165]
	v_pk_fma_f32 v[166:167], v[20:21], v[158:159], v[166:167]
	v_pk_fma_f32 v[168:169], v[22:23], v[160:161], v[168:169]
	v_pk_fma_f32 v[162:163], v[24:25], v[128:129], v[162:163]
	v_pk_fma_f32 v[164:165], v[26:27], v[130:131], v[164:165]
	v_pk_fma_f32 v[166:167], v[28:29], v[132:133], v[166:167]
	v_pk_fma_f32 v[168:169], v[30:31], v[134:135], v[168:169]
	v_pk_fma_f32 v[162:163], v[32:33], v[136:137], v[162:163]
	v_pk_fma_f32 v[164:165], v[34:35], v[138:139], v[164:165]
	v_pk_fma_f32 v[166:167], v[36:37], v[140:141], v[166:167]
	v_pk_fma_f32 v[168:169], v[38:39], v[142:143], v[168:169]
	v_pk_mul_f32 v[40:41], v[162:163], s[12:13]
	v_pk_mul_f32 v[42:43], v[164:165], s[12:13]
	v_pk_mul_f32 v[44:45], v[166:167], s[12:13]
	v_pk_mul_f32 v[46:47], v[168:169], s[12:13]
	v_exp_f32_e32 v40, v40
	v_exp_f32_e32 v41, v41
	v_exp_f32_e32 v42, v42
	v_exp_f32_e32 v43, v43
	v_exp_f32_e32 v44, v44
	v_exp_f32_e32 v45, v45
	v_exp_f32_e32 v46, v46
	v_exp_f32_e32 v47, v47
	v_pk_add_f32 v[40:41], v[40:41], s[14:15]
	v_pk_add_f32 v[42:43], v[42:43], s[14:15]
	v_pk_add_f32 v[44:45], v[44:45], s[14:15]
	v_pk_add_f32 v[46:47], v[46:47], s[14:15]
	v_rcp_f32_e32 v40, v40
	v_rcp_f32_e32 v41, v41
	v_rcp_f32_e32 v42, v42
	v_rcp_f32_e32 v43, v43
	v_rcp_f32_e32 v44, v44
	v_rcp_f32_e32 v45, v45
	v_rcp_f32_e32 v46, v46
	v_rcp_f32_e32 v47, v47
	v_pk_mul_f32 v[162:163], v[162:163], v[40:41]
	v_pk_mul_f32 v[164:165], v[164:165], v[42:43]
	v_pk_mul_f32 v[166:167], v[166:167], v[44:45]
	v_pk_mul_f32 v[168:169], v[168:169], v[46:47]
	v_pk_mul_f32 v[40:41], v[162:163], v[162:163]
	v_pk_fma_f32 v[40:41], v[164:165], v[164:165], v[40:41]
	v_pk_fma_f32 v[40:41], v[166:167], v[166:167], v[40:41]
	v_pk_fma_f32 v[40:41], v[168:169], v[168:169], v[40:41]
	s_nop 0
	v_add_f32_e32 v50, v40, v41
	s_nop 1
	v_add_f32_dpp v50, v50, v50 quad_perm:[1,0,3,2] row_mask:0xf bank_mask:0xf
	s_nop 1
	v_add_f32_dpp v50, v50, v50 quad_perm:[2,3,0,1] row_mask:0xf bank_mask:0xf
	s_nop 1
	v_add_f32_dpp v50, v50, v50 row_half_mirror row_mask:0xf bank_mask:0xf
	s_nop 1
	v_add_f32_dpp v50, v50, v50 row_mirror row_mask:0xf bank_mask:0xf
	v_add_f32_e32 v50, 0x358637bd, v50
	v_rsq_f32_e32 v50, v50
	s_nop 0
	v_pk_mul_f32 v[162:163], v[162:163], v[50:51] op_sel_hi:[1,0]
	v_pk_mul_f32 v[164:165], v[164:165], v[50:51] op_sel_hi:[1,0]
	v_pk_mul_f32 v[166:167], v[166:167], v[50:51] op_sel_hi:[1,0]
	v_pk_mul_f32 v[168:169], v[168:169], v[50:51] op_sel_hi:[1,0]
	v_cvt_pk_bf16_f32 v170, v162, v163
	v_cvt_pk_bf16_f32 v171, v164, v165
	v_cvt_pk_bf16_f32 v172, v166, v167
	v_cvt_pk_bf16_f32 v173, v168, v169
	global_store_dwordx4 v5, v[170:173], s[6:7]
	s_add_u32 s6, s6, 0x800
	s_addc_u32 s7, s7, 0
	s_waitcnt vmcnt(26)
; __device__ __forceinline__ unsigned pk2(float lo, float hi) { const f32v2_t v = {lo, hi}; const bf16v2_t b = __builtin_convertvector(v, bf16v2_t); return __builtin_bit_cast(unsigned, b); }
; __device__ __forceinline__ float lo16(unsigned u) { return __uint_as_float(u << 16); }
; __device__ __forceinline__ float hi16(unsigned u) { return __uint_as_float(u & 0xffff0000u); }
; __device__ __forceinline__ float siluf_(float x) { return x * __builtin_amdgcn_rcpf(1.0f + __expf(-x)); }
; __device__ __forceinline__ void prep_dn_load(const bf16_t* proj, const float* cw, int idx, u32x4 (&raw)[4], int& t, int& ch) {
;     if (idx >= 0) { t = idx / 384; const int j = idx - t * 384; ch = j * 8; }
; #pragma unroll
;     for (int k = 0; k < 4; ++k) { const int tt = t - 3 + k; raw[k] = (u32x4){0u, 0u, 0u, 0u};
;         if (tt >= 0) raw[k] = *(const u32x4*)(proj + (size_t)tt * NP + C_DNQ + ch); }
; }
; __device__ __forceinline__ void prep_dn_finish(const float* cw, bf16_t* dq, bf16_t* dk, bf16_t* dv, const u32x4 (&raw)[4], int t, int ch) {
;     float a[8];
; #pragma unroll
;     for (int e = 0; e < 8; ++e) a[e] = 0.f;
; #pragma unroll
;     for (int k = 0; k < 4; ++k) {
;         const f32x4 w0 = *(const f32x4*)(cw + k * 3072 + ch), w1 = *(const f32x4*)(cw + k * 3072 + ch + 4);
;         a[0] += w0[0] * lo16(raw[k].x); a[1] += w0[1] * hi16(raw[k].x); a[2] += w0[2] * lo16(raw[k].y); a[3] += w0[3] * hi16(raw[k].y);
;         a[4] += w1[0] * lo16(raw[k].z); a[5] += w1[1] * hi16(raw[k].z); a[6] += w1[2] * lo16(raw[k].w); a[7] += w1[3] * hi16(raw[k].w); }
;     float ss = 0.f;
; #pragma unroll
;     for (int e = 0; e < 8; ++e) { a[e] = siluf_(a[e]); ss += a[e] * a[e]; }
;     ss += __shfl_xor(ss, 1); ss += __shfl_xor(ss, 2); ss += __shfl_xor(ss, 4); ss += __shfl_xor(ss, 8);
;     float sc = 1.0f;
;     if (ch < 2048) { sc = rsqrtf(ss + EPS); if (ch < 1024) sc *= 0.08838834764831845f; }
;     u32x4 w; w.x = pk2(a[0] * sc, a[1] * sc); w.y = pk2(a[2] * sc, a[3] * sc); w.z = pk2(a[4] * sc, a[5] * sc); w.w = pk2(a[6] * sc, a[7] * sc);
;     bf16_t* dst = (ch < 1024) ? dq : (ch < 2048 ? dk : dv);
;     *(u32x4*)(dst + (size_t)t * 1024 + (ch & 1023)) = w;
; }
	v_lshlrev_b32_e32 v146, 16, v92
	v_and_b32_e32 v147, 0xffff0000, v92
	v_lshlrev_b32_e32 v148, 16, v93
	v_and_b32_e32 v149, 0xffff0000, v93
	v_lshlrev_b32_e32 v150, 16, v94
	v_and_b32_e32 v151, 0xffff0000, v94
	v_lshlrev_b32_e32 v152, 16, v95
	v_and_b32_e32 v153, 0xffff0000, v95
	global_load_dwordx4 v[92:95], v2, s[100:101]
	s_sub_u32 s100, s100, 0x4ec00
	s_subb_u32 s101, s101, 0
	v_pk_mul_f32 v[162:163], v[8:9], v[154:155]
	v_pk_mul_f32 v[164:165], v[10:11], v[156:157]
	v_pk_mul_f32 v[166:167], v[12:13], v[158:159]
	v_pk_mul_f32 v[168:169], v[14:15], v[160:161]
	v_pk_fma_f32 v[162:163], v[16:17], v[128:129], v[162:163]
	v_pk_fma_f32 v[164:165], v[18:19], v[130:131], v[164:165]
	v_pk_fma_f32 v[166:167], v[20:21], v[132:133], v[166:167]
	v_pk_fma_f32 v[168:169], v[22:23], v[134:135], v[168:169]
	v_pk_fma_f32 v[162:163], v[24:25], v[136:137], v[162:163]
	v_pk_fma_f32 v[164:165], v[26:27], v[138:139], v[164:165]
	v_pk_fma_f32 v[166:167], v[28:29], v[140:141], v[166:167]
	v_pk_fma_f32 v[168:169], v[30:31], v[142:143], v[168:169]
	v_pk_fma_f32 v[162:163], v[32:33], v[146:147], v[162:163]
	v_pk_fma_f32 v[164:165], v[34:35], v[148:149], v[164:165]
	v_pk_fma_f32 v[166:167], v[36:37], v[150:151], v[166:167]
	v_pk_fma_f32 v[168:169], v[38:39], v[152:153], v[168:169]
	v_pk_mul_f32 v[40:41], v[162:163], s[12:13]
	v_pk_mul_f32 v[42:43], v[164:165], s[12:13]
	v_pk_mul_f32 v[44:45], v[166:167], s[12:13]
	v_pk_mul_f32 v[46:47], v[168:169], s[12:13]
	v_exp_f32_e32 v40, v40
	v_exp_f32_e32 v41, v41
	v_exp_f32_e32 v42, v42
	v_exp_f32_e32 v43, v43
	v_exp_f32_e32 v44, v44
	v_exp_f32_e32 v45, v45
	v_exp_f32_e32 v46, v46
	v_exp_f32_e32 v47, v47
	v_pk_add_f32 v[40:41], v[40:41], s[14:15]
	v_pk_add_f32 v[42:43], v[42:43], s[14:15]
	v_pk_add_f32 v[44:45], v[44:45], s[14:15]
	v_pk_add_f32 v[46:47], v[46:47], s[14:15]
	v_rcp_f32_e32 v40, v40
	v_rcp_f32_e32 v41, v41
	v_rcp_f32_e32 v42, v42
	v_rcp_f32_e32 v43, v43
	v_rcp_f32_e32 v44, v44
	v_rcp_f32_e32 v45, v45
	v_rcp_f32_e32 v46, v46
	v_rcp_f32_e32 v47, v47
	v_pk_mul_f32 v[162:163], v[162:163], v[40:41]
	v_pk_mul_f32 v[164:165], v[164:165], v[42:43]
	v_pk_mul_f32 v[166:167], v[166:167], v[44:45]
	v_pk_mul_f32 v[168:169], v[168:169], v[46:47]
	v_pk_mul_f32 v[40:41], v[162:163], v[162:163]
	v_pk_fma_f32 v[40:41], v[164:165], v[164:165], v[40:41]
	v_pk_fma_f32 v[40:41], v[166:167], v[166:167], v[40:41]
	v_pk_fma_f32 v[40:41], v[168:169], v[168:169], v[40:41]
	s_nop 0
	v_add_f32_e32 v50, v40, v41
	s_nop 1
	v_add_f32_dpp v50, v50, v50 quad_perm:[1,0,3,2] row_mask:0xf bank_mask:0xf
	s_nop 1
	v_add_f32_dpp v50, v50, v50 quad_perm:[2,3,0,1] row_mask:0xf bank_mask:0xf
	s_nop 1
	v_add_f32_dpp v50, v50, v50 row_half_mirror row_mask:0xf bank_mask:0xf
	s_nop 1
	v_add_f32_dpp v50, v50, v50 row_mirror row_mask:0xf bank_mask:0xf
	v_add_f32_e32 v50, 0x358637bd, v50
	v_rsq_f32_e32 v50, v50
	s_nop 0
	v_pk_mul_f32 v[162:163], v[162:163], v[50:51] op_sel_hi:[1,0]
	v_pk_mul_f32 v[164:165], v[164:165], v[50:51] op_sel_hi:[1,0]
	v_pk_mul_f32 v[166:167], v[166:167], v[50:51] op_sel_hi:[1,0]
	v_pk_mul_f32 v[168:169], v[168:169], v[50:51] op_sel_hi:[1,0]
	v_cvt_pk_bf16_f32 v170, v162, v163
	v_cvt_pk_bf16_f32 v171, v164, v165
	v_cvt_pk_bf16_f32 v172, v166, v167
	v_cvt_pk_bf16_f32 v173, v168, v169
	global_store_dwordx4 v5, v[170:173], s[6:7]
	s_sub_u32 s6, s6, 0x3800
	s_subb_u32 s7, s7, 0
	s_waitcnt vmcnt(16)
	s_cmp_lt_i32 s10, 0
	s_cbranch_scc0 .Ldnc_nz2
	v_mov_b32_e32 v52, 0
	v_mov_b32_e32 v53, 0
	v_mov_b32_e32 v54, 0
	v_mov_b32_e32 v55, 0
	v_mov_b32_e32 v56, 0
	v_mov_b32_e32 v57, 0
	v_mov_b32_e32 v58, 0
	v_mov_b32_e32 v59, 0
	v_mov_b32_e32 v60, 0
	v_mov_b32_e32 v61, 0
	v_mov_b32_e32 v62, 0
	v_mov_b32_e32 v63, 0
.Ldnc_nz2:
	v_lshlrev_b32_e32 v128, 16, v52
	v_and_b32_e32 v129, 0xffff0000, v52
	v_lshlrev_b32_e32 v130, 16, v53
	v_and_b32_e32 v131, 0xffff0000, v53
	v_lshlrev_b32_e32 v132, 16, v54
	v_and_b32_e32 v133, 0xffff0000, v54
	v_lshlrev_b32_e32 v134, 16, v55
	v_and_b32_e32 v135, 0xffff0000, v55
	v_lshlrev_b32_e32 v136, 16, v56
	v_and_b32_e32 v137, 0xffff0000, v56
	v_lshlrev_b32_e32 v138, 16, v57
	v_and_b32_e32 v139, 0xffff0000, v57
	v_lshlrev_b32_e32 v140, 16, v58
	v_and_b32_e32 v141, 0xffff0000, v58
	v_lshlrev_b32_e32 v142, 16, v59
	v_and_b32_e32 v143, 0xffff0000, v59
	v_lshlrev_b32_e32 v146, 16, v60
	v_and_b32_e32 v147, 0xffff0000, v60
	v_lshlrev_b32_e32 v148, 16, v61
	v_and_b32_e32 v149, 0xffff0000, v61
	v_lshlrev_b32_e32 v150, 16, v62
	v_and_b32_e32 v151, 0xffff0000, v62
	v_lshlrev_b32_e32 v152, 16, v63
	v_and_b32_e32 v153, 0xffff0000, v63
	s_waitcnt vmcnt(15)
; __device__ __forceinline__ unsigned pk2(float lo, float hi) { const f32v2_t v = {lo, hi}; const bf16v2_t b = __builtin_convertvector(v, bf16v2_t); return __builtin_bit_cast(unsigned, b); }
; __device__ __forceinline__ float lo16(unsigned u) { return __uint_as_float(u << 16); }
; __device__ __forceinline__ float hi16(unsigned u) { return __uint_as_float(u & 0xffff0000u); }
; __device__ __forceinline__ float siluf_(float x) { return x * __builtin_amdgcn_rcpf(1.0f + __expf(-x)); }
; __device__ __forceinline__ void prep_dn_finish(const float* cw, bf16_t* dq, bf16_t* dk, bf16_t* dv, const u32x4 (&raw)[4], int t, int ch) {
;     float a[8];
; #pragma unroll
;     for (int e = 0; e < 8; ++e) a[e] = 0.f;
; #pragma unroll
;     for (int k = 0; k < 4; ++k) {
;         const f32x4 w0 = *(const f32x4*)(cw + k * 3072 + ch), w1 = *(const f32x4*)(cw + k * 3072 + ch + 4);
;         a[0] += w0[0] * lo16(raw[k].x); a[1] += w0[1] * hi16(raw[k].x); a[2] += w0[2] * lo16(raw[k].y); a[3] += w0[3] * hi16(raw[k].y);
;         a[4] += w1[0] * lo16(raw[k].z); a[5] += w1[1] * hi16(raw[k].z); a[6] += w1[2] * lo16(raw[k].w); a[7] += w1[3] * hi16(raw[k].w); }
;     float ss = 0.f;
; #pragma unroll
;     for (int e = 0; e < 8; ++e) { a[e] = siluf_(a[e]); ss += a[e] * a[e]; }
;     ss += __shfl_xor(ss, 1); ss += __shfl_xor(ss, 2); ss += __shfl_xor(ss, 4); ss += __shfl_xor(ss, 8);
;     float sc = 1.0f;
;     if (ch < 2048) { sc = rsqrtf(ss + EPS); if (ch < 1024) sc *= 0.08838834764831845f; }
;     u32x4 w; w.x = pk2(a[0] * sc, a[1] * sc); w.y = pk2(a[2] * sc, a[3] * sc); w.z = pk2(a[4] * sc, a[5] * sc); w.w = pk2(a[6] * sc, a[7] * sc);
;     bf16_t* dst = (ch < 1024) ? dq : (ch < 2048 ? dk : dv);
;     *(u32x4*)(dst + (size_t)t * 1024 + (ch & 1023)) = w;
; }
	v_lshlrev_b32_e32 v154, 16, v64
	v_and_b32_e32 v155, 0xffff0000, v64
	v_lshlrev_b32_e32 v156, 16, v65
	v_and_b32_e32 v157, 0xffff0000, v65
	v_lshlrev_b32_e32 v158, 16, v66
	v_and_b32_e32 v159, 0xffff0000, v66
	v_lshlrev_b32_e32 v160, 16, v67
	v_and_b32_e32 v161, 0xffff0000, v67
	v_pk_mul_f32 v[162:163], v[96:97], v[128:129]
	v_pk_mul_f32 v[164:165], v[98:99], v[130:131]
	v_pk_mul_f32 v[166:167], v[100:101], v[132:133]
	v_pk_mul_f32 v[168:169], v[102:103], v[134:135]
	v_pk_fma_f32 v[162:163], v[104:105], v[136:137], v[162:163]
	v_pk_fma_f32 v[164:165], v[106:107], v[138:139], v[164:165]
	v_pk_fma_f32 v[166:167], v[108:109], v[140:141], v[166:167]
	v_pk_fma_f32 v[168:169], v[110:111], v[142:143], v[168:169]
	v_pk_fma_f32 v[162:163], v[112:113], v[146:147], v[162:163]
	v_pk_fma_f32 v[164:165], v[114:115], v[148:149], v[164:165]
	v_pk_fma_f32 v[166:167], v[116:117], v[150:151], v[166:167]
	v_pk_fma_f32 v[168:169], v[118:119], v[152:153], v[168:169]
	v_pk_fma_f32 v[162:163], v[120:121], v[154:155], v[162:163]
	v_pk_fma_f32 v[164:165], v[122:123], v[156:157], v[164:165]
	v_pk_fma_f32 v[166:167], v[124:125], v[158:159], v[166:167]
	v_pk_fma_f32 v[168:169], v[126:127], v[160:161], v[168:169]
	v_pk_mul_f32 v[40:41], v[162:163], s[12:13]
	v_pk_mul_f32 v[42:43], v[164:165], s[12:13]
	v_pk_mul_f32 v[44:45], v[166:167], s[12:13]
	v_pk_mul_f32 v[46:47], v[168:169], s[12:13]
	v_exp_f32_e32 v40, v40
	v_exp_f32_e32 v41, v41
	v_exp_f32_e32 v42, v42
	v_exp_f32_e32 v43, v43
	v_exp_f32_e32 v44, v44
	v_exp_f32_e32 v45, v45
	v_exp_f32_e32 v46, v46
	v_exp_f32_e32 v47, v47
	v_pk_add_f32 v[40:41], v[40:41], s[14:15]
	v_pk_add_f32 v[42:43], v[42:43], s[14:15]
	v_pk_add_f32 v[44:45], v[44:45], s[14:15]
	v_pk_add_f32 v[46:47], v[46:47], s[14:15]
	v_rcp_f32_e32 v40, v40
	v_rcp_f32_e32 v41, v41
	v_rcp_f32_e32 v42, v42
	v_rcp_f32_e32 v43, v43
	v_rcp_f32_e32 v44, v44
	v_rcp_f32_e32 v45, v45
	v_rcp_f32_e32 v46, v46
	v_rcp_f32_e32 v47, v47
	v_pk_mul_f32 v[162:163], v[162:163], v[40:41]
	v_pk_mul_f32 v[164:165], v[164:165], v[42:43]
	v_pk_mul_f32 v[166:167], v[166:167], v[44:45]
	v_pk_mul_f32 v[168:169], v[168:169], v[46:47]
	v_cvt_pk_bf16_f32 v170, v162, v163
	v_cvt_pk_bf16_f32 v171, v164, v165
	v_cvt_pk_bf16_f32 v172, v166, v167
	v_cvt_pk_bf16_f32 v173, v168, v169
	global_store_dwordx4 v6, v[170:173], s[6:7]
	s_add_u32 s6, s6, 0x800
	s_addc_u32 s7, s7, 0
	s_waitcnt vmcnt(14)
	v_lshlrev_b32_e32 v128, 16, v68
	v_and_b32_e32 v129, 0xffff0000, v68
	v_lshlrev_b32_e32 v130, 16, v69
	v_and_b32_e32 v131, 0xffff0000, v69
	v_lshlrev_b32_e32 v132, 16, v70
	v_and_b32_e32 v133, 0xffff0000, v70
	v_lshlrev_b32_e32 v134, 16, v71
	v_and_b32_e32 v135, 0xffff0000, v71
	v_pk_mul_f32 v[162:163], v[96:97], v[136:137]
	v_pk_mul_f32 v[164:165], v[98:99], v[138:139]
	v_pk_mul_f32 v[166:167], v[100:101], v[140:141]
	v_pk_mul_f32 v[168:169], v[102:103], v[142:143]
	v_pk_fma_f32 v[162:163], v[104:105], v[146:147], v[162:163]
	v_pk_fma_f32 v[164:165], v[106:107], v[148:149], v[164:165]
	v_pk_fma_f32 v[166:167], v[108:109], v[150:151], v[166:167]
	v_pk_fma_f32 v[168:169], v[110:111], v[152:153], v[168:169]
	v_pk_fma_f32 v[162:163], v[112:113], v[154:155], v[162:163]
	v_pk_fma_f32 v[164:165], v[114:115], v[156:157], v[164:165]
	v_pk_fma_f32 v[166:167], v[116:117], v[158:159], v[166:167]
	v_pk_fma_f32 v[168:169], v[118:119], v[160:161], v[168:169]
	v_pk_fma_f32 v[162:163], v[120:121], v[128:129], v[162:163]
	v_pk_fma_f32 v[164:165], v[122:123], v[130:131], v[164:165]
	v_pk_fma_f32 v[166:167], v[124:125], v[132:133], v[166:167]
	v_pk_fma_f32 v[168:169], v[126:127], v[134:135], v[168:169]
	v_pk_mul_f32 v[40:41], v[162:163], s[12:13]
	v_pk_mul_f32 v[42:43], v[164:165], s[12:13]
	v_pk_mul_f32 v[44:45], v[166:167], s[12:13]
	v_pk_mul_f32 v[46:47], v[168:169], s[12:13]
	v_exp_f32_e32 v40, v40
	v_exp_f32_e32 v41, v41
	v_exp_f32_e32 v42, v42
	v_exp_f32_e32 v43, v43
	v_exp_f32_e32 v44, v44
	v_exp_f32_e32 v45, v45
	v_exp_f32_e32 v46, v46
	v_exp_f32_e32 v47, v47
	v_pk_add_f32 v[40:41], v[40:41], s[14:15]
	v_pk_add_f32 v[42:43], v[42:43], s[14:15]
	v_pk_add_f32 v[44:45], v[44:45], s[14:15]
	v_pk_add_f32 v[46:47], v[46:47], s[14:15]
	v_rcp_f32_e32 v40, v40
	v_rcp_f32_e32 v41, v41
	v_rcp_f32_e32 v42, v42
	v_rcp_f32_e32 v43, v43
	v_rcp_f32_e32 v44, v44
	v_rcp_f32_e32 v45, v45
	v_rcp_f32_e32 v46, v46
	v_rcp_f32_e32 v47, v47
	v_pk_mul_f32 v[162:163], v[162:163], v[40:41]
	v_pk_mul_f32 v[164:165], v[164:165], v[42:43]
	v_pk_mul_f32 v[166:167], v[166:167], v[44:45]
	v_pk_mul_f32 v[168:169], v[168:169], v[46:47]
	v_cvt_pk_bf16_f32 v170, v162, v163
	v_cvt_pk_bf16_f32 v171, v164, v165
	v_cvt_pk_bf16_f32 v172, v166, v167
	v_cvt_pk_bf16_f32 v173, v168, v169
	global_store_dwordx4 v6, v[170:173], s[6:7]
	s_add_u32 s6, s6, 0x800
	s_addc_u32 s7, s7, 0
	s_waitcnt vmcnt(13)
; __device__ __forceinline__ unsigned pk2(float lo, float hi) { const f32v2_t v = {lo, hi}; const bf16v2_t b = __builtin_convertvector(v, bf16v2_t); return __builtin_bit_cast(unsigned, b); }
; __device__ __forceinline__ float lo16(unsigned u) { return __uint_as_float(u << 16); }
; __device__ __forceinline__ float hi16(unsigned u) { return __uint_as_float(u & 0xffff0000u); }
; __device__ __forceinline__ float siluf_(float x) { return x * __builtin_amdgcn_rcpf(1.0f + __expf(-x)); }
; __device__ __forceinline__ void prep_dn_finish(const float* cw, bf16_t* dq, bf16_t* dk, bf16_t* dv, const u32x4 (&raw)[4], int t, int ch) {
;     float a[8];
; #pragma unroll
;     for (int e = 0; e < 8; ++e) a[e] = 0.f;
; #pragma unroll
;     for (int k = 0; k < 4; ++k) {
;         const f32x4 w0 = *(const f32x4*)(cw + k * 3072 + ch), w1 = *(const f32x4*)(cw + k * 3072 + ch + 4);
;         a[0] += w0[0] * lo16(raw[k].x); a[1] += w0[1] * hi16(raw[k].x); a[2] += w0[2] * lo16(raw[k].y); a[3] += w0[3] * hi16(raw[k].y);
;         a[4] += w1[0] * lo16(raw[k].z); a[5] += w1[1] * hi16(raw[k].z); a[6] += w1[2] * lo16(raw[k].w); a[7] += w1[3] * hi16(raw[k].w); }
;     float ss = 0.f;
; #pragma unroll
;     for (int e = 0; e < 8; ++e) { a[e] = siluf_(a[e]); ss += a[e] * a[e]; }
;     ss += __shfl_xor(ss, 1); ss += __shfl_xor(ss, 2); ss += __shfl_xor(ss, 4); ss += __shfl_xor(ss, 8);
;     float sc = 1.0f;
;     if (ch < 2048) { sc = rsqrtf(ss + EPS); if (ch < 1024) sc *= 0.08838834764831845f; }
;     u32x4 w; w.x = pk2(a[0] * sc, a[1] * sc); w.y = pk2(a[2] * sc, a[3] * sc); w.z = pk2(a[4] * sc, a[5] * sc); w.w = pk2(a[6] * sc, a[7] * sc);
;     bf16_t* dst = (ch < 1024) ? dq : (ch < 2048 ? dk : dv);
;     *(u32x4*)(dst + (size_t)t * 1024 + (ch & 1023)) = w;
; }
	v_lshlrev_b32_e32 v136, 16, v72
	v_and_b32_e32 v137, 0xffff0000, v72
	v_lshlrev_b32_e32 v138, 16, v73
	v_and_b32_e32 v139, 0xffff0000, v73
	v_lshlrev_b32_e32 v140, 16, v74
	v_and_b32_e32 v141, 0xffff0000, v74
	v_lshlrev_b32_e32 v142, 16, v75
	v_and_b32_e32 v143, 0xffff0000, v75
	v_pk_mul_f32 v[162:163], v[96:97], v[146:147]
	v_pk_mul_f32 v[164:165], v[98:99], v[148:149]
	v_pk_mul_f32 v[166:167], v[100:101], v[150:151]
	v_pk_mul_f32 v[168:169], v[102:103], v[152:153]
	v_pk_fma_f32 v[162:163], v[104:105], v[154:155], v[162:163]
	v_pk_fma_f32 v[164:165], v[106:107], v[156:157], v[164:165]
	v_pk_fma_f32 v[166:167], v[108:109], v[158:159], v[166:167]
	v_pk_fma_f32 v[168:169], v[110:111], v[160:161], v[168:169]
	v_pk_fma_f32 v[162:163], v[112:113], v[128:129], v[162:163]
	v_pk_fma_f32 v[164:165], v[114:115], v[130:131], v[164:165]
	v_pk_fma_f32 v[166:167], v[116:117], v[132:133], v[166:167]
	v_pk_fma_f32 v[168:169], v[118:119], v[134:135], v[168:169]
	v_pk_fma_f32 v[162:163], v[120:121], v[136:137], v[162:163]
	v_pk_fma_f32 v[164:165], v[122:123], v[138:139], v[164:165]
	v_pk_fma_f32 v[166:167], v[124:125], v[140:141], v[166:167]
	v_pk_fma_f32 v[168:169], v[126:127], v[142:143], v[168:169]
	v_pk_mul_f32 v[40:41], v[162:163], s[12:13]
	v_pk_mul_f32 v[42:43], v[164:165], s[12:13]
	v_pk_mul_f32 v[44:45], v[166:167], s[12:13]
	v_pk_mul_f32 v[46:47], v[168:169], s[12:13]
	v_exp_f32_e32 v40, v40
	v_exp_f32_e32 v41, v41
	v_exp_f32_e32 v42, v42
	v_exp_f32_e32 v43, v43
	v_exp_f32_e32 v44, v44
	v_exp_f32_e32 v45, v45
	v_exp_f32_e32 v46, v46
	v_exp_f32_e32 v47, v47
	v_pk_add_f32 v[40:41], v[40:41], s[14:15]
	v_pk_add_f32 v[42:43], v[42:43], s[14:15]
	v_pk_add_f32 v[44:45], v[44:45], s[14:15]
	v_pk_add_f32 v[46:47], v[46:47], s[14:15]
	v_rcp_f32_e32 v40, v40
	v_rcp_f32_e32 v41, v41
	v_rcp_f32_e32 v42, v42
	v_rcp_f32_e32 v43, v43
	v_rcp_f32_e32 v44, v44
	v_rcp_f32_e32 v45, v45
	v_rcp_f32_e32 v46, v46
	v_rcp_f32_e32 v47, v47
	v_pk_mul_f32 v[162:163], v[162:163], v[40:41]
	v_pk_mul_f32 v[164:165], v[164:165], v[42:43]
	v_pk_mul_f32 v[166:167], v[166:167], v[44:45]
	v_pk_mul_f32 v[168:169], v[168:169], v[46:47]
	v_cvt_pk_bf16_f32 v170, v162, v163
	v_cvt_pk_bf16_f32 v171, v164, v165
	v_cvt_pk_bf16_f32 v172, v166, v167
	v_cvt_pk_bf16_f32 v173, v168, v169
	global_store_dwordx4 v6, v[170:173], s[6:7]
	s_add_u32 s6, s6, 0x800
	s_addc_u32 s7, s7, 0
	s_waitcnt vmcnt(12)
	v_lshlrev_b32_e32 v146, 16, v76
	v_and_b32_e32 v147, 0xffff0000, v76
	v_lshlrev_b32_e32 v148, 16, v77
	v_and_b32_e32 v149, 0xffff0000, v77
	v_lshlrev_b32_e32 v150, 16, v78
	v_and_b32_e32 v151, 0xffff0000, v78
	v_lshlrev_b32_e32 v152, 16, v79
	v_and_b32_e32 v153, 0xffff0000, v79
	v_pk_mul_f32 v[162:163], v[96:97], v[154:155]
	v_pk_mul_f32 v[164:165], v[98:99], v[156:157]
	v_pk_mul_f32 v[166:167], v[100:101], v[158:159]
	v_pk_mul_f32 v[168:169], v[102:103], v[160:161]
	v_pk_fma_f32 v[162:163], v[104:105], v[128:129], v[162:163]
	v_pk_fma_f32 v[164:165], v[106:107], v[130:131], v[164:165]
	v_pk_fma_f32 v[166:167], v[108:109], v[132:133], v[166:167]
	v_pk_fma_f32 v[168:169], v[110:111], v[134:135], v[168:169]
	v_pk_fma_f32 v[162:163], v[112:113], v[136:137], v[162:163]
	v_pk_fma_f32 v[164:165], v[114:115], v[138:139], v[164:165]
	v_pk_fma_f32 v[166:167], v[116:117], v[140:141], v[166:167]
	v_pk_fma_f32 v[168:169], v[118:119], v[142:143], v[168:169]
	v_pk_fma_f32 v[162:163], v[120:121], v[146:147], v[162:163]
	v_pk_fma_f32 v[164:165], v[122:123], v[148:149], v[164:165]
	v_pk_fma_f32 v[166:167], v[124:125], v[150:151], v[166:167]
	v_pk_fma_f32 v[168:169], v[126:127], v[152:153], v[168:169]
	v_pk_mul_f32 v[40:41], v[162:163], s[12:13]
	v_pk_mul_f32 v[42:43], v[164:165], s[12:13]
	v_pk_mul_f32 v[44:45], v[166:167], s[12:13]
	v_pk_mul_f32 v[46:47], v[168:169], s[12:13]
	v_exp_f32_e32 v40, v40
	v_exp_f32_e32 v41, v41
	v_exp_f32_e32 v42, v42
	v_exp_f32_e32 v43, v43
	v_exp_f32_e32 v44, v44
	v_exp_f32_e32 v45, v45
	v_exp_f32_e32 v46, v46
	v_exp_f32_e32 v47, v47
	v_pk_add_f32 v[40:41], v[40:41], s[14:15]
	v_pk_add_f32 v[42:43], v[42:43], s[14:15]
	v_pk_add_f32 v[44:45], v[44:45], s[14:15]
	v_pk_add_f32 v[46:47], v[46:47], s[14:15]
	v_rcp_f32_e32 v40, v40
	v_rcp_f32_e32 v41, v41
	v_rcp_f32_e32 v42, v42
	v_rcp_f32_e32 v43, v43
	v_rcp_f32_e32 v44, v44
	v_rcp_f32_e32 v45, v45
	v_rcp_f32_e32 v46, v46
	v_rcp_f32_e32 v47, v47
	v_pk_mul_f32 v[162:163], v[162:163], v[40:41]
	v_pk_mul_f32 v[164:165], v[164:165], v[42:43]
	v_pk_mul_f32 v[166:167], v[166:167], v[44:45]
	v_pk_mul_f32 v[168:169], v[168:169], v[46:47]
	v_cvt_pk_bf16_f32 v170, v162, v163
	v_cvt_pk_bf16_f32 v171, v164, v165
	v_cvt_pk_bf16_f32 v172, v166, v167
	v_cvt_pk_bf16_f32 v173, v168, v169
	global_store_dwordx4 v6, v[170:173], s[6:7]
	s_add_u32 s6, s6, 0x800
	s_addc_u32 s7, s7, 0
	s_waitcnt vmcnt(11)
; __device__ __forceinline__ unsigned pk2(float lo, float hi) { const f32v2_t v = {lo, hi}; const bf16v2_t b = __builtin_convertvector(v, bf16v2_t); return __builtin_bit_cast(unsigned, b); }
; __device__ __forceinline__ float lo16(unsigned u) { return __uint_as_float(u << 16); }
; __device__ __forceinline__ float hi16(unsigned u) { return __uint_as_float(u & 0xffff0000u); }
; __device__ __forceinline__ float siluf_(float x) { return x * __builtin_amdgcn_rcpf(1.0f + __expf(-x)); }
; __device__ __forceinline__ void prep_dn_finish(const float* cw, bf16_t* dq, bf16_t* dk, bf16_t* dv, const u32x4 (&raw)[4], int t, int ch) {
;     float a[8];
; #pragma unroll
;     for (int e = 0; e < 8; ++e) a[e] = 0.f;
; #pragma unroll
;     for (int k = 0; k < 4; ++k) {
;         const f32x4 w0 = *(const f32x4*)(cw + k * 3072 + ch), w1 = *(const f32x4*)(cw + k * 3072 + ch + 4);
;         a[0] += w0[0] * lo16(raw[k].x); a[1] += w0[1] * hi16(raw[k].x); a[2] += w0[2] * lo16(raw[k].y); a[3] += w0[3] * hi16(raw[k].y);
;         a[4] += w1[0] * lo16(raw[k].z); a[5] += w1[1] * hi16(raw[k].z); a[6] += w1[2] * lo16(raw[k].w); a[7] += w1[3] * hi16(raw[k].w); }
;     float ss = 0.f;
; #pragma unroll
;     for (int e = 0; e < 8; ++e) { a[e] = siluf_(a[e]); ss += a[e] * a[e]; }
;     ss += __shfl_xor(ss, 1); ss += __shfl_xor(ss, 2); ss += __shfl_xor(ss, 4); ss += __shfl_xor(ss, 8);
;     float sc = 1.0f;
;     if (ch < 2048) { sc = rsqrtf(ss + EPS); if (ch < 1024) sc *= 0.08838834764831845f; }
;     u32x4 w; w.x = pk2(a[0] * sc, a[1] * sc); w.y = pk2(a[2] * sc, a[3] * sc); w.z = pk2(a[4] * sc, a[5] * sc); w.w = pk2(a[6] * sc, a[7] * sc);
;     bf16_t* dst = (ch < 1024) ? dq : (ch < 2048 ? dk : dv);
;     *(u32x4*)(dst + (size_t)t * 1024 + (ch & 1023)) = w;
; }
	v_lshlrev_b32_e32 v154, 16, v80
	v_and_b32_e32 v155, 0xffff0000, v80
	v_lshlrev_b32_e32 v156, 16, v81
	v_and_b32_e32 v157, 0xffff0000, v81
	v_lshlrev_b32_e32 v158, 16, v82
	v_and_b32_e32 v159, 0xffff0000, v82
	v_lshlrev_b32_e32 v160, 16, v83
	v_and_b32_e32 v161, 0xffff0000, v83
	v_pk_mul_f32 v[162:163], v[96:97], v[128:129]
	v_pk_mul_f32 v[164:165], v[98:99], v[130:131]
	v_pk_mul_f32 v[166:167], v[100:101], v[132:133]
	v_pk_mul_f32 v[168:169], v[102:103], v[134:135]
	v_pk_fma_f32 v[162:163], v[104:105], v[136:137], v[162:163]
	v_pk_fma_f32 v[164:165], v[106:107], v[138:139], v[164:165]
	v_pk_fma_f32 v[166:167], v[108:109], v[140:141], v[166:167]
	v_pk_fma_f32 v[168:169], v[110:111], v[142:143], v[168:169]
	v_pk_fma_f32 v[162:163], v[112:113], v[146:147], v[162:163]
	v_pk_fma_f32 v[164:165], v[114:115], v[148:149], v[164:165]
	v_pk_fma_f32 v[166:167], v[116:117], v[150:151], v[166:167]
	v_pk_fma_f32 v[168:169], v[118:119], v[152:153], v[168:169]
	v_pk_fma_f32 v[162:163], v[120:121], v[154:155], v[162:163]
	v_pk_fma_f32 v[164:165], v[122:123], v[156:157], v[164:165]
	v_pk_fma_f32 v[166:167], v[124:125], v[158:159], v[166:167]
	v_pk_fma_f32 v[168:169], v[126:127], v[160:161], v[168:169]
	v_pk_mul_f32 v[40:41], v[162:163], s[12:13]
	v_pk_mul_f32 v[42:43], v[164:165], s[12:13]
	v_pk_mul_f32 v[44:45], v[166:167], s[12:13]
	v_pk_mul_f32 v[46:47], v[168:169], s[12:13]
	v_exp_f32_e32 v40, v40
	v_exp_f32_e32 v41, v41
	v_exp_f32_e32 v42, v42
	v_exp_f32_e32 v43, v43
	v_exp_f32_e32 v44, v44
	v_exp_f32_e32 v45, v45
	v_exp_f32_e32 v46, v46
	v_exp_f32_e32 v47, v47
	v_pk_add_f32 v[40:41], v[40:41], s[14:15]
	v_pk_add_f32 v[42:43], v[42:43], s[14:15]
	v_pk_add_f32 v[44:45], v[44:45], s[14:15]
	v_pk_add_f32 v[46:47], v[46:47], s[14:15]
	v_rcp_f32_e32 v40, v40
	v_rcp_f32_e32 v41, v41
	v_rcp_f32_e32 v42, v42
	v_rcp_f32_e32 v43, v43
	v_rcp_f32_e32 v44, v44
	v_rcp_f32_e32 v45, v45
	v_rcp_f32_e32 v46, v46
	v_rcp_f32_e32 v47, v47
	v_pk_mul_f32 v[162:163], v[162:163], v[40:41]
	v_pk_mul_f32 v[164:165], v[164:165], v[42:43]
	v_pk_mul_f32 v[166:167], v[166:167], v[44:45]
	v_pk_mul_f32 v[168:169], v[168:169], v[46:47]
	v_cvt_pk_bf16_f32 v170, v162, v163
	v_cvt_pk_bf16_f32 v171, v164, v165
	v_cvt_pk_bf16_f32 v172, v166, v167
	v_cvt_pk_bf16_f32 v173, v168, v169
	global_store_dwordx4 v6, v[170:173], s[6:7]
	s_add_u32 s6, s6, 0x800
	s_addc_u32 s7, s7, 0
	s_waitcnt vmcnt(10)
	v_lshlrev_b32_e32 v128, 16, v84
	v_and_b32_e32 v129, 0xffff0000, v84
	v_lshlrev_b32_e32 v130, 16, v85
	v_and_b32_e32 v131, 0xffff0000, v85
	v_lshlrev_b32_e32 v132, 16, v86
	v_and_b32_e32 v133, 0xffff0000, v86
	v_lshlrev_b32_e32 v134, 16, v87
	v_and_b32_e32 v135, 0xffff0000, v87
	v_pk_mul_f32 v[162:163], v[96:97], v[136:137]
	v_pk_mul_f32 v[164:165], v[98:99], v[138:139]
	v_pk_mul_f32 v[166:167], v[100:101], v[140:141]
	v_pk_mul_f32 v[168:169], v[102:103], v[142:143]
	v_pk_fma_f32 v[162:163], v[104:105], v[146:147], v[162:163]
	v_pk_fma_f32 v[164:165], v[106:107], v[148:149], v[164:165]
	v_pk_fma_f32 v[166:167], v[108:109], v[150:151], v[166:167]
	v_pk_fma_f32 v[168:169], v[110:111], v[152:153], v[168:169]
	v_pk_fma_f32 v[162:163], v[112:113], v[154:155], v[162:163]
	v_pk_fma_f32 v[164:165], v[114:115], v[156:157], v[164:165]
	v_pk_fma_f32 v[166:167], v[116:117], v[158:159], v[166:167]
	v_pk_fma_f32 v[168:169], v[118:119], v[160:161], v[168:169]
	v_pk_fma_f32 v[162:163], v[120:121], v[128:129], v[162:163]
	v_pk_fma_f32 v[164:165], v[122:123], v[130:131], v[164:165]
	v_pk_fma_f32 v[166:167], v[124:125], v[132:133], v[166:167]
	v_pk_fma_f32 v[168:169], v[126:127], v[134:135], v[168:169]
	v_pk_mul_f32 v[40:41], v[162:163], s[12:13]
	v_pk_mul_f32 v[42:43], v[164:165], s[12:13]
	v_pk_mul_f32 v[44:45], v[166:167], s[12:13]
	v_pk_mul_f32 v[46:47], v[168:169], s[12:13]
	v_exp_f32_e32 v40, v40
	v_exp_f32_e32 v41, v41
	v_exp_f32_e32 v42, v42
	v_exp_f32_e32 v43, v43
	v_exp_f32_e32 v44, v44
	v_exp_f32_e32 v45, v45
	v_exp_f32_e32 v46, v46
	v_exp_f32_e32 v47, v47
	v_pk_add_f32 v[40:41], v[40:41], s[14:15]
	v_pk_add_f32 v[42:43], v[42:43], s[14:15]
	v_pk_add_f32 v[44:45], v[44:45], s[14:15]
	v_pk_add_f32 v[46:47], v[46:47], s[14:15]
	v_rcp_f32_e32 v40, v40
	v_rcp_f32_e32 v41, v41
	v_rcp_f32_e32 v42, v42
	v_rcp_f32_e32 v43, v43
	v_rcp_f32_e32 v44, v44
	v_rcp_f32_e32 v45, v45
	v_rcp_f32_e32 v46, v46
	v_rcp_f32_e32 v47, v47
	v_pk_mul_f32 v[162:163], v[162:163], v[40:41]
	v_pk_mul_f32 v[164:165], v[164:165], v[42:43]
	v_pk_mul_f32 v[166:167], v[166:167], v[44:45]
	v_pk_mul_f32 v[168:169], v[168:169], v[46:47]
	v_cvt_pk_bf16_f32 v170, v162, v163
	v_cvt_pk_bf16_f32 v171, v164, v165
	v_cvt_pk_bf16_f32 v172, v166, v167
	v_cvt_pk_bf16_f32 v173, v168, v169
	global_store_dwordx4 v6, v[170:173], s[6:7]
	s_add_u32 s6, s6, 0x800
	s_addc_u32 s7, s7, 0
	s_waitcnt vmcnt(9)
; __device__ __forceinline__ unsigned pk2(float lo, float hi) { const f32v2_t v = {lo, hi}; const bf16v2_t b = __builtin_convertvector(v, bf16v2_t); return __builtin_bit_cast(unsigned, b); }
; __device__ __forceinline__ float lo16(unsigned u) { return __uint_as_float(u << 16); }
; __device__ __forceinline__ float hi16(unsigned u) { return __uint_as_float(u & 0xffff0000u); }
; __device__ __forceinline__ float siluf_(float x) { return x * __builtin_amdgcn_rcpf(1.0f + __expf(-x)); }
; __device__ __forceinline__ void prep_dn_finish(const float* cw, bf16_t* dq, bf16_t* dk, bf16_t* dv, const u32x4 (&raw)[4], int t, int ch) {
;     float a[8];
; #pragma unroll
;     for (int e = 0; e < 8; ++e) a[e] = 0.f;
; #pragma unroll
;     for (int k = 0; k < 4; ++k) {
;         const f32x4 w0 = *(const f32x4*)(cw + k * 3072 + ch), w1 = *(const f32x4*)(cw + k * 3072 + ch + 4);
;         a[0] += w0[0] * lo16(raw[k].x); a[1] += w0[1] * hi16(raw[k].x); a[2] += w0[2] * lo16(raw[k].y); a[3] += w0[3] * hi16(raw[k].y);
;         a[4] += w1[0] * lo16(raw[k].z); a[5] += w1[1] * hi16(raw[k].z); a[6] += w1[2] * lo16(raw[k].w); a[7] += w1[3] * hi16(raw[k].w); }
;     float ss = 0.f;
; #pragma unroll
;     for (int e = 0; e < 8; ++e) { a[e] = siluf_(a[e]); ss += a[e] * a[e]; }
;     ss += __shfl_xor(ss, 1); ss += __shfl_xor(ss, 2); ss += __shfl_xor(ss, 4); ss += __shfl_xor(ss, 8);
;     float sc = 1.0f;
;     if (ch < 2048) { sc = rsqrtf(ss + EPS); if (ch < 1024) sc *= 0.08838834764831845f; }
;     u32x4 w; w.x = pk2(a[0] * sc, a[1] * sc); w.y = pk2(a[2] * sc, a[3] * sc); w.z = pk2(a[4] * sc, a[5] * sc); w.w = pk2(a[6] * sc, a[7] * sc);
;     bf16_t* dst = (ch < 1024) ? dq : (ch < 2048 ? dk : dv);
;     *(u32x4*)(dst + (size_t)t * 1024 + (ch & 1023)) = w;
; }
	v_lshlrev_b32_e32 v136, 16, v88
	v_and_b32_e32 v137, 0xffff0000, v88
	v_lshlrev_b32_e32 v138, 16, v89
	v_and_b32_e32 v139, 0xffff0000, v89
	v_lshlrev_b32_e32 v140, 16, v90
	v_and_b32_e32 v141, 0xffff0000, v90
	v_lshlrev_b32_e32 v142, 16, v91
	v_and_b32_e32 v143, 0xffff0000, v91
	v_pk_mul_f32 v[162:163], v[96:97], v[146:147]
	v_pk_mul_f32 v[164:165], v[98:99], v[148:149]
	v_pk_mul_f32 v[166:167], v[100:101], v[150:151]
	v_pk_mul_f32 v[168:169], v[102:103], v[152:153]
	v_pk_fma_f32 v[162:163], v[104:105], v[154:155], v[162:163]
	v_pk_fma_f32 v[164:165], v[106:107], v[156:157], v[164:165]
	v_pk_fma_f32 v[166:167], v[108:109], v[158:159], v[166:167]
	v_pk_fma_f32 v[168:169], v[110:111], v[160:161], v[168:169]
	v_pk_fma_f32 v[162:163], v[112:113], v[128:129], v[162:163]
	v_pk_fma_f32 v[164:165], v[114:115], v[130:131], v[164:165]
	v_pk_fma_f32 v[166:167], v[116:117], v[132:133], v[166:167]
	v_pk_fma_f32 v[168:169], v[118:119], v[134:135], v[168:169]
	v_pk_fma_f32 v[162:163], v[120:121], v[136:137], v[162:163]
	v_pk_fma_f32 v[164:165], v[122:123], v[138:139], v[164:165]
	v_pk_fma_f32 v[166:167], v[124:125], v[140:141], v[166:167]
	v_pk_fma_f32 v[168:169], v[126:127], v[142:143], v[168:169]
	v_pk_mul_f32 v[40:41], v[162:163], s[12:13]
	v_pk_mul_f32 v[42:43], v[164:165], s[12:13]
	v_pk_mul_f32 v[44:45], v[166:167], s[12:13]
	v_pk_mul_f32 v[46:47], v[168:169], s[12:13]
	v_exp_f32_e32 v40, v40
	v_exp_f32_e32 v41, v41
	v_exp_f32_e32 v42, v42
	v_exp_f32_e32 v43, v43
	v_exp_f32_e32 v44, v44
	v_exp_f32_e32 v45, v45
	v_exp_f32_e32 v46, v46
	v_exp_f32_e32 v47, v47
	v_pk_add_f32 v[40:41], v[40:41], s[14:15]
	v_pk_add_f32 v[42:43], v[42:43], s[14:15]
	v_pk_add_f32 v[44:45], v[44:45], s[14:15]
	v_pk_add_f32 v[46:47], v[46:47], s[14:15]
	v_rcp_f32_e32 v40, v40
	v_rcp_f32_e32 v41, v41
	v_rcp_f32_e32 v42, v42
	v_rcp_f32_e32 v43, v43
	v_rcp_f32_e32 v44, v44
	v_rcp_f32_e32 v45, v45
	v_rcp_f32_e32 v46, v46
	v_rcp_f32_e32 v47, v47
	v_pk_mul_f32 v[162:163], v[162:163], v[40:41]
	v_pk_mul_f32 v[164:165], v[164:165], v[42:43]
	v_pk_mul_f32 v[166:167], v[166:167], v[44:45]
	v_pk_mul_f32 v[168:169], v[168:169], v[46:47]
	v_cvt_pk_bf16_f32 v170, v162, v163
	v_cvt_pk_bf16_f32 v171, v164, v165
	v_cvt_pk_bf16_f32 v172, v166, v167
	v_cvt_pk_bf16_f32 v173, v168, v169
	global_store_dwordx4 v6, v[170:173], s[6:7]
	s_add_u32 s6, s6, 0x800
	s_addc_u32 s7, s7, 0
	s_waitcnt vmcnt(8)
	v_lshlrev_b32_e32 v146, 16, v92
	v_and_b32_e32 v147, 0xffff0000, v92
	v_lshlrev_b32_e32 v148, 16, v93
	v_and_b32_e32 v149, 0xffff0000, v93
	v_lshlrev_b32_e32 v150, 16, v94
	v_and_b32_e32 v151, 0xffff0000, v94
	v_lshlrev_b32_e32 v152, 16, v95
	v_and_b32_e32 v153, 0xffff0000, v95
	v_pk_mul_f32 v[162:163], v[96:97], v[154:155]
	v_pk_mul_f32 v[164:165], v[98:99], v[156:157]
	v_pk_mul_f32 v[166:167], v[100:101], v[158:159]
	v_pk_mul_f32 v[168:169], v[102:103], v[160:161]
	v_pk_fma_f32 v[162:163], v[104:105], v[128:129], v[162:163]
	v_pk_fma_f32 v[164:165], v[106:107], v[130:131], v[164:165]
	v_pk_fma_f32 v[166:167], v[108:109], v[132:133], v[166:167]
	v_pk_fma_f32 v[168:169], v[110:111], v[134:135], v[168:169]
	v_pk_fma_f32 v[162:163], v[112:113], v[136:137], v[162:163]
	v_pk_fma_f32 v[164:165], v[114:115], v[138:139], v[164:165]
	v_pk_fma_f32 v[166:167], v[116:117], v[140:141], v[166:167]
	v_pk_fma_f32 v[168:169], v[118:119], v[142:143], v[168:169]
	v_pk_fma_f32 v[162:163], v[120:121], v[146:147], v[162:163]
	v_pk_fma_f32 v[164:165], v[122:123], v[148:149], v[164:165]
	v_pk_fma_f32 v[166:167], v[124:125], v[150:151], v[166:167]
	v_pk_fma_f32 v[168:169], v[126:127], v[152:153], v[168:169]
	v_pk_mul_f32 v[40:41], v[162:163], s[12:13]
	v_pk_mul_f32 v[42:43], v[164:165], s[12:13]
	v_pk_mul_f32 v[44:45], v[166:167], s[12:13]
	v_pk_mul_f32 v[46:47], v[168:169], s[12:13]
	v_exp_f32_e32 v40, v40
	v_exp_f32_e32 v41, v41
	v_exp_f32_e32 v42, v42
	v_exp_f32_e32 v43, v43
	v_exp_f32_e32 v44, v44
	v_exp_f32_e32 v45, v45
	v_exp_f32_e32 v46, v46
	v_exp_f32_e32 v47, v47
	v_pk_add_f32 v[40:41], v[40:41], s[14:15]
	v_pk_add_f32 v[42:43], v[42:43], s[14:15]
	v_pk_add_f32 v[44:45], v[44:45], s[14:15]
	v_pk_add_f32 v[46:47], v[46:47], s[14:15]
	v_rcp_f32_e32 v40, v40
	v_rcp_f32_e32 v41, v41
	v_rcp_f32_e32 v42, v42
	v_rcp_f32_e32 v43, v43
	v_rcp_f32_e32 v44, v44
	v_rcp_f32_e32 v45, v45
	v_rcp_f32_e32 v46, v46
	v_rcp_f32_e32 v47, v47
	v_pk_mul_f32 v[162:163], v[162:163], v[40:41]
	v_pk_mul_f32 v[164:165], v[164:165], v[42:43]
	v_pk_mul_f32 v[166:167], v[166:167], v[44:45]
	v_pk_mul_f32 v[168:169], v[168:169], v[46:47]
	v_cvt_pk_bf16_f32 v170, v162, v163
	v_cvt_pk_bf16_f32 v171, v164, v165
	v_cvt_pk_bf16_f32 v172, v166, v167
	v_cvt_pk_bf16_f32 v173, v168, v169
	global_store_dwordx4 v6, v[170:173], s[6:7]
	s_sub_u32 s6, s6, 0x3800
	s_subb_u32 s7, s7, 0
	s_mov_b64 s[6:7], exec
